# conv weights + s5_gemm B tiles (P1 and P3) staged per task in LDS with coalesced loads; fragments read via ds_read_b128
# speedup vs baseline: 1.1494x; 1.0149x over previous
.LBB0_323:
	s_and_b64 vcc, exec, s[2:3]
	s_cbranch_vccz .LBB0_327
	s_add_i32 s2, s14, 0xfde0
	s_and_b32 s3, s2, 0xffff
	s_mul_i32 s3, s3, 0xf0f1
	s_lshr_b32 s4, s3, 20
	s_mul_i32 s5, s4, 17
	s_sub_i32 s5, s2, s5
	v_mov_b32_e32 v1, v0
	s_and_b32 s6, s5, 0xffff
	s_lshr_b32 s2, s3, 12
	s_and_b32 s3, s2, 0xff00
	s_waitcnt vmcnt(0)
	v_and_b32_e32 v10, 15, v1
	v_and_b32_e32 v2, 0xffffffcf, v1
	s_mul_i32 s2, s4, 0x4400
	s_lshl_b32 s6, s6, 10
	s_lshl_b32 s88, s4, 18
	v_ashrrev_i32_e32 v3, 31, v2
	v_lshlrev_b32_e32 v118, 4, v10
	s_add_i32 s4, s2, s6
	v_lshlrev_b64 v[4:5], 10, v[2:3]
	v_and_b32_e32 v11, 48, v1
	v_or_b32_e32 v8, s4, v118
	v_lshl_or_b32 v3, v8, 5, v11
	v_lshl_add_u64 v[4:5], s[88:89], 0, v[4:5]
	v_or_b32_e32 v130, 0x6000, v3
	v_or_b32_e32 v4, v4, v11
	v_lshl_add_u64 v[70:71], s[86:87], 0, v[130:131]
	v_or_b32_e32 v130, 0x4000, v3
	v_lshl_add_u64 v[78:79], s[86:87], 0, v[4:5]
	v_or_b32_e32 v4, 16, v2
	v_or_b32_e32 v2, 32, v2
	v_lshl_add_u64 v[72:73], s[86:87], 0, v[130:131]
	v_or_b32_e32 v130, 0x2000, v3
	v_ashrrev_i32_e32 v3, 31, v2
	v_or_b32_e32 v6, 48, v1
	v_lshlrev_b64 v[2:3], 10, v[2:3]
	v_ashrrev_i32_e32 v7, 31, v6
	v_lshl_add_u64 v[2:3], s[88:89], 0, v[2:3]
	v_lshlrev_b64 v[6:7], 10, v[6:7]
	v_or_b32_e32 v2, v2, v11
	s_lshl_b32 s4, s5, 19
	v_lshl_add_u64 v[82:83], s[86:87], 0, v[2:3]
	v_lshl_add_u64 v[2:3], s[88:89], 0, v[6:7]
	s_or_b32 s3, s4, s3
	v_lshl_add_u64 v[74:75], s[86:87], 0, v[130:131]
	v_or_b32_e32 v2, v2, v11
	v_lshl_add_u32 v130, v10, 13, s3
	v_lshl_add_u64 v[84:85], s[86:87], 0, v[2:3]
	v_lshlrev_b64 v[2:3], 1, v[130:131]
	v_or_b32_e32 v2, v2, v11
	v_lshl_add_u64 v[86:87], s[86:87], 0, v[2:3]
	v_add_u32_e32 v2, 0x20000, v130
	v_mov_b32_e32 v3, v131
	v_lshlrev_b64 v[2:3], 1, v[2:3]
	v_or_b32_e32 v2, v2, v11
	v_lshl_add_u64 v[88:89], s[86:87], 0, v[2:3]
	v_or_b32_e32 v2, 0x40000, v130
	v_mov_b32_e32 v3, v131
	v_ashrrev_i32_e32 v5, 31, v4
	v_lshlrev_b64 v[2:3], 1, v[2:3]
	v_mov_b32_e32 v9, v131
	v_lshlrev_b64 v[4:5], 10, v[4:5]
	v_or_b32_e32 v2, v2, v11
	v_add_u32_e32 v130, 0x60000, v130
	v_lshlrev_b64 v[8:9], 5, v[8:9]
	v_lshl_add_u64 v[4:5], s[88:89], 0, v[4:5]
	v_lshl_add_u64 v[90:91], s[86:87], 0, v[2:3]
	v_lshlrev_b64 v[2:3], 1, v[130:131]
	v_or_b32_e32 v8, v8, v11
	v_or_b32_e32 v4, v4, v11
	v_or_b32_e32 v2, v2, v11
	v_mov_b32_e32 v18, 0
	v_lshrrev_b32_e32 v119, 4, v1
	v_lshl_add_u64 v[76:77], s[86:87], 0, v[8:9]
	v_lshl_add_u64 v[80:81], s[86:87], 0, v[4:5]
	v_lshl_add_u64 v[92:93], s[86:87], 0, v[2:3]
	s_lshr_b32 s62, s88, 18
	s_mul_i32 s64, s62, 0x88000
	s_and_b32 s65, s5, 0xffff
	s_lshl_b32 s65, s65, 15
	s_add_u32 s64, s64, s65
	s_add_u32 s98, s86, s64
	s_addc_u32 s99, s87, 0
	s_add_u32 s98, s98, 0x2bf1100
	s_addc_u32 s99, s99, 0
	s_and_b32 s64, s5, 0xffff
	s_lshl_b32 s64, s64, 20
	s_lshl_b32 s65, s62, 9
	s_add_u32 s64, s64, s65
	s_add_u32 s62, s86, s64
	s_addc_u32 s63, s87, 0
	s_add_u32 s62, s62, 0x80f1100
	s_addc_u32 s63, s63, 0
	v_lshrrev_b32_e32 v226, 6, v1
	v_and_b32_e32 v227, 31, v1
	v_lshlrev_b32_e32 v227, 4, v227
	v_lshl_add_u32 v228, v226, 9, v227
	v_lshl_add_u32 v229, v226, 14, v227
	v_and_b32_e32 v230, 32, v1
	v_cmp_ne_u32_e32 vcc, 0, v230
	v_mov_b32_e32 v231, s98
	v_mov_b32_e32 v232, s99
	v_mov_b32_e32 v233, s62
	v_mov_b32_e32 v234, s63
	v_cndmask_b32_e32 v228, v228, v229, vcc
	v_cndmask_b32_e32 v224, v231, v233, vcc
	v_cndmask_b32_e32 v225, v232, v234, vcc
	v_mov_b32_e32 v229, 0
	v_lshl_add_u64 v[224:225], v[224:225], 0, v[228:229]
	v_mov_b32_e32 v230, 0x800
	v_mov_b32_e32 v231, 0x10000
	v_cndmask_b32_e32 v228, v230, v231, vcc
	v_and_b32_e32 v227, 63, v1
	v_lshlrev_b32_e32 v227, 4, v227
	s_movk_i32 s64, 0x410
	v_mad_u32_u24 v226, v226, s64, v227
	v_and_b32_e32 v222, 15, v1
	v_mul_u32_u24_e32 v222, 0x410, v222
	v_bfe_u32 v227, v1, 4, 2
	v_lshl_add_u32 v222, v227, 4, v222
	global_load_dwordx4 v[2:5], v[224:225], off
	v_lshl_add_u64 v[224:225], v[224:225], 0, v[228:229]
	global_load_dwordx4 v[6:9], v[224:225], off
	v_lshl_add_u64 v[224:225], v[224:225], 0, v[228:229]
	global_load_dwordx4 v[10:13], v[224:225], off
	v_lshl_add_u64 v[224:225], v[224:225], 0, v[228:229]
	global_load_dwordx4 v[14:17], v[224:225], off
	v_lshl_add_u64 v[224:225], v[224:225], 0, v[228:229]
	global_load_dwordx4 v[20:23], v[224:225], off
	v_lshl_add_u64 v[224:225], v[224:225], 0, v[228:229]
	global_load_dwordx4 v[24:27], v[224:225], off
	v_lshl_add_u64 v[224:225], v[224:225], 0, v[228:229]
	global_load_dwordx4 v[28:31], v[224:225], off
	v_lshl_add_u64 v[224:225], v[224:225], 0, v[228:229]
	global_load_dwordx4 v[32:35], v[224:225], off
	v_lshl_add_u64 v[224:225], v[224:225], 0, v[228:229]
	global_load_dwordx4 v[36:39], v[224:225], off
	v_lshl_add_u64 v[224:225], v[224:225], 0, v[228:229]
	global_load_dwordx4 v[40:43], v[224:225], off
	v_lshl_add_u64 v[224:225], v[224:225], 0, v[228:229]
	global_load_dwordx4 v[44:47], v[224:225], off
	v_lshl_add_u64 v[224:225], v[224:225], 0, v[228:229]
	global_load_dwordx4 v[48:51], v[224:225], off
	v_lshl_add_u64 v[224:225], v[224:225], 0, v[228:229]
	global_load_dwordx4 v[52:55], v[224:225], off
	v_lshl_add_u64 v[224:225], v[224:225], 0, v[228:229]
	global_load_dwordx4 v[56:59], v[224:225], off
	v_lshl_add_u64 v[224:225], v[224:225], 0, v[228:229]
	global_load_dwordx4 v[60:63], v[224:225], off
	v_lshl_add_u64 v[224:225], v[224:225], 0, v[228:229]
	global_load_dwordx4 v[64:67], v[224:225], off
	s_waitcnt vmcnt(0)
	ds_write_b128 v226, v[2:5]
	ds_write_b128 v226, v[6:9] offset:4160
	ds_write_b128 v226, v[10:13] offset:8320
	ds_write_b128 v226, v[14:17] offset:12480
	ds_write_b128 v226, v[20:23] offset:16640
	ds_write_b128 v226, v[24:27] offset:20800
	ds_write_b128 v226, v[28:31] offset:24960
	ds_write_b128 v226, v[32:35] offset:29120
	ds_write_b128 v226, v[36:39] offset:33280
	ds_write_b128 v226, v[40:43] offset:37440
	ds_write_b128 v226, v[44:47] offset:41600
	ds_write_b128 v226, v[48:51] offset:45760
	ds_write_b128 v226, v[52:55] offset:49920
	ds_write_b128 v226, v[56:59] offset:54080
	ds_write_b128 v226, v[60:63] offset:58240
	ds_write_b128 v226, v[64:67] offset:62400
	s_waitcnt lgkmcnt(0)
	s_barrier
	s_mov_b32 s3, 0
	s_mov_b64 s[4:5], 0
	v_mov_b32_e32 v19, v18
	v_mov_b32_e32 v20, v18
	v_mov_b32_e32 v21, v18
	v_mov_b32_e32 v22, v18
	v_mov_b32_e32 v23, v18
	v_mov_b32_e32 v24, v18
	v_mov_b32_e32 v25, v18
	v_mov_b32_e32 v26, v18
	v_mov_b32_e32 v27, v18
	v_mov_b32_e32 v28, v18
	v_mov_b32_e32 v29, v18
	v_mov_b32_e32 v30, v18
	v_mov_b32_e32 v31, v18
	v_mov_b32_e32 v32, v18
	v_mov_b32_e32 v33, v18
	v_mov_b32_e32 v34, v18
	v_mov_b32_e32 v35, v18
	v_mov_b32_e32 v36, v18
	v_mov_b32_e32 v37, v18
	v_mov_b32_e32 v38, v18
	v_mov_b32_e32 v39, v18
	v_mov_b32_e32 v40, v18
	v_mov_b32_e32 v41, v18
	v_mov_b32_e32 v42, v18
	v_mov_b32_e32 v43, v18
	v_mov_b32_e32 v44, v18
	v_mov_b32_e32 v45, v18
	v_mov_b32_e32 v46, v18
	v_mov_b32_e32 v47, v18
	v_mov_b32_e32 v48, v18
	v_mov_b32_e32 v49, v18
	v_mov_b32_e32 v50, v18
	v_mov_b32_e32 v51, v18
	v_mov_b32_e32 v52, v18
	v_mov_b32_e32 v53, v18
	v_mov_b32_e32 v54, v18
	v_mov_b32_e32 v55, v18
	v_mov_b32_e32 v56, v18
	v_mov_b32_e32 v57, v18
	v_mov_b32_e32 v58, v18
	v_mov_b32_e32 v59, v18
	v_mov_b32_e32 v60, v18
	v_mov_b32_e32 v61, v18
	v_mov_b32_e32 v62, v18
	v_mov_b32_e32 v63, v18
	v_mov_b32_e32 v64, v18
	v_mov_b32_e32 v65, v18
	v_mov_b32_e32 v14, v18
	v_mov_b32_e32 v15, v18
	v_mov_b32_e32 v16, v18
	v_mov_b32_e32 v17, v18
	v_mov_b32_e32 v10, v18
	v_mov_b32_e32 v11, v18
	v_mov_b32_e32 v12, v18
	v_mov_b32_e32 v13, v18
	v_mov_b32_e32 v6, v18
	v_mov_b32_e32 v7, v18
	v_mov_b32_e32 v8, v18
	v_mov_b32_e32 v9, v18
	v_mov_b32_e32 v2, v18
	v_mov_b32_e32 v3, v18
	v_mov_b32_e32 v4, v18
	v_mov_b32_e32 v5, v18
	s_mov_b64 s[0:1], 0x2bf1100
	s_mov_b32 s7, 0x9b71000
	s_mov_b64 s[8:9], 0x80f0f00
	s_mov_b64 s[10:11], 0x2bf1140
	s_mov_b64 s[16:17], 0x80f0f40
.LBB0_325:
	v_lshl_add_u64 v[158:159], v[78:79], 0, s[4:5]
	v_add_co_u32_e32 v130, vcc, s7, v158
	v_lshl_add_u64 v[162:163], v[80:81], 0, s[4:5]
	s_nop 0
	v_addc_co_u32_e32 v134, vcc, 0, v159, vcc
	v_add_co_u32_e32 v137, vcc, s7, v162
	s_cmp_lt_u32 s3, 8
	s_nop 0
	v_addc_co_u32_e32 v158, vcc, 0, v163, vcc
	v_lshl_add_u64 v[162:163], v[82:83], 0, s[4:5]
	v_add_co_u32_e32 v159, vcc, s7, v162
	v_lshl_add_u64 v[164:165], v[86:87], 0, s[4:5]
	s_nop 0
	v_addc_co_u32_e32 v160, vcc, 0, v163, vcc
	v_lshl_add_u64 v[162:163], v[84:85], 0, s[4:5]
	v_add_co_u32_e32 v166, vcc, s7, v162
	s_nop 1
	v_addc_co_u32_e32 v168, vcc, 0, v163, vcc
	v_lshl_add_u64 v[162:163], v[76:77], 0, s[4:5]
	s_cselect_b64 vcc, -1, 0
	v_lshl_add_u64 v[170:171], v[74:75], 0, s[4:5]
	v_lshl_add_u64 v[174:175], v[88:89], 0, s[4:5]
	v_lshl_add_u64 v[176:177], v[72:73], 0, s[4:5]
	v_lshl_add_u64 v[180:181], v[90:91], 0, s[4:5]
	v_lshl_add_u64 v[182:183], v[70:71], 0, s[4:5]
	v_lshl_add_u64 v[184:185], v[92:93], 0, s[4:5]
	v_lshl_add_u64 v[186:187], v[162:163], 0, s[10:11]
	v_lshl_add_u64 v[162:163], v[164:165], 0, s[16:17]
	v_lshl_add_u64 v[164:165], v[184:185], 0, s[16:17]
	v_cndmask_b32_e32 v169, v163, v187, vcc
	v_cndmask_b32_e32 v172, v162, v186, vcc
	v_mov_b32_e32 v162, v130
	v_mov_b32_e32 v163, v134
	global_load_dwordx4 v[184:187], v[162:163], off offset:320
	v_mov_b32_e32 v162, v137
	v_mov_b32_e32 v163, v158
	global_load_dwordx4 v[188:191], v[162:163], off offset:320
	v_mov_b32_e32 v162, v159
	v_mov_b32_e32 v163, v160
	global_load_dwordx4 v[192:195], v[162:163], off offset:320
	v_mov_b32_e32 v158, v166
	v_mov_b32_e32 v159, v168
	global_load_dwordx4 v[212:215], v[158:159], off offset:320
	v_lshl_add_u64 v[158:159], v[170:171], 0, s[10:11]
	v_lshl_add_u64 v[162:163], v[174:175], 0, s[16:17]
	v_lshl_add_u64 v[170:171], v[176:177], 0, s[10:11]
	v_lshl_add_u64 v[174:175], v[180:181], 0, s[16:17]
	v_lshl_add_u64 v[176:177], v[182:183], 0, s[10:11]
	v_cndmask_b32_e32 v130, v163, v159, vcc
	v_cndmask_b32_e32 v134, v162, v158, vcc
	v_cndmask_b32_e32 v137, v175, v171, vcc
	v_cndmask_b32_e32 v158, v174, v170, vcc
	v_cndmask_b32_e32 v159, v165, v177, vcc
	v_cndmask_b32_e32 v160, v164, v176, vcc
	v_mov_b32_e32 v162, v172
	v_mov_b32_e32 v163, v169
	ds_read_b128 v[174:177], v222 offset:64
	v_mov_b32_e32 v162, v134
	v_mov_b32_e32 v163, v130
	ds_read_b128 v[168:171], v222 offset:16704
	v_mov_b32_e32 v162, v158
	v_mov_b32_e32 v163, v137
	ds_read_b128 v[180:183], v222 offset:33344
	v_mov_b32_e32 v162, v160
	v_mov_b32_e32 v163, v159
	ds_read_b128 v[218:221], v222 offset:49984
	v_lshl_add_u64 v[66:67], v[78:79], 0, s[4:5]
	v_add_co_u32_e32 v116, vcc, s7, v66
	v_lshl_add_u64 v[94:95], v[80:81], 0, s[4:5]
	s_nop 0
	v_addc_co_u32_e32 v117, vcc, 0, v67, vcc
	v_add_co_u32_e32 v114, vcc, s7, v94
	s_cmp_lt_u32 s3, 8
	s_nop 0
	v_addc_co_u32_e32 v115, vcc, 0, v95, vcc
	v_lshl_add_u64 v[94:95], v[82:83], 0, s[4:5]
	v_add_co_u32_e32 v98, vcc, s7, v94
	v_lshl_add_u64 v[96:97], v[86:87], 0, s[4:5]
	s_nop 0
	v_addc_co_u32_e32 v99, vcc, 0, v95, vcc
	v_lshl_add_u64 v[94:95], v[84:85], 0, s[4:5]
	v_add_co_u32_e32 v102, vcc, s7, v94
	v_lshl_add_u64 v[104:105], v[96:97], 0, s[8:9]
	s_nop 0
	v_addc_co_u32_e32 v103, vcc, 0, v95, vcc
	v_lshl_add_u64 v[94:95], v[76:77], 0, s[4:5]
	s_cselect_b64 vcc, -1, 0
	v_lshl_add_u64 v[100:101], v[94:95], 0, s[0:1]
	v_cndmask_b32_e32 v101, v105, v101, vcc
	v_cndmask_b32_e32 v100, v104, v100, vcc
	ds_read_b128 v[142:145], v222
	v_lshl_add_u64 v[100:101], v[74:75], 0, s[4:5]
	v_lshl_add_u64 v[104:105], v[88:89], 0, s[4:5]
	v_lshl_add_u64 v[106:107], v[100:101], 0, s[0:1]
	v_lshl_add_u64 v[108:109], v[104:105], 0, s[8:9]
	v_cndmask_b32_e32 v107, v109, v107, vcc
	v_cndmask_b32_e32 v106, v108, v106, vcc
	ds_read_b128 v[146:149], v222 offset:16640
	v_lshl_add_u64 v[106:107], v[72:73], 0, s[4:5]
	v_lshl_add_u64 v[110:111], v[90:91], 0, s[4:5]
	v_lshl_add_u64 v[108:109], v[106:107], 0, s[0:1]
	v_lshl_add_u64 v[112:113], v[110:111], 0, s[8:9]
	global_load_dwordx4 v[66:69], v[116:117], off offset:256
	global_load_dwordx4 v[120:123], v[114:115], off offset:256
	global_load_dwordx4 v[124:127], v[98:99], off offset:256
	v_cndmask_b32_e32 v109, v113, v109, vcc
	v_cndmask_b32_e32 v108, v112, v108, vcc
	ds_read_b128 v[150:153], v222 offset:33280
	v_lshl_add_u64 v[112:113], v[70:71], 0, s[4:5]
	v_lshl_add_u64 v[108:109], v[92:93], 0, s[4:5]
	v_lshl_add_u64 v[128:129], v[112:113], 0, s[0:1]
	v_lshl_add_u64 v[154:155], v[108:109], 0, s[8:9]
	v_cndmask_b32_e32 v129, v155, v129, vcc
	v_cndmask_b32_e32 v128, v154, v128, vcc
	ds_read_b128 v[154:157], v222 offset:49920
	global_load_dwordx4 v[138:141], v[102:103], off offset:256
	v_lshl_add_u64 v[94:95], v[94:95], 0, s[10:11]
	v_lshl_add_u64 v[96:97], v[96:97], 0, s[16:17]
	v_lshl_add_u64 v[108:109], v[108:109], 0, s[16:17]
	v_cndmask_b32_e32 v95, v97, v95, vcc
	v_cndmask_b32_e32 v94, v96, v94, vcc
	s_add_i32 s3, s3, 2
	s_add_u32 s4, s4, 0x80
	s_addc_u32 s5, s5, 0
	s_cmpk_lg_i32 s4, 0x400
	s_waitcnt vmcnt(0) lgkmcnt(0)
	v_mfma_f32_16x16x32_bf16 v[62:65], v[66:69], v[142:145], v[62:65]
	v_mfma_f32_16x16x32_bf16 v[58:61], v[66:69], v[146:149], v[58:61]
	s_waitcnt vmcnt(2)
	v_mfma_f32_16x16x32_bf16 v[54:57], v[66:69], v[150:153], v[54:57]
	s_waitcnt vmcnt(1)
	v_mfma_f32_16x16x32_bf16 v[50:53], v[66:69], v[154:157], v[50:53]
	v_mfma_f32_16x16x32_bf16 v[46:49], v[120:123], v[142:145], v[46:49]
	v_mfma_f32_16x16x32_bf16 v[42:45], v[120:123], v[146:149], v[42:45]
	v_mfma_f32_16x16x32_bf16 v[38:41], v[120:123], v[150:153], v[38:41]
	v_mfma_f32_16x16x32_bf16 v[34:37], v[120:123], v[154:157], v[34:37]
	v_mfma_f32_16x16x32_bf16 v[30:33], v[124:127], v[142:145], v[30:33]
	v_mfma_f32_16x16x32_bf16 v[26:29], v[124:127], v[146:149], v[26:29]
	v_mfma_f32_16x16x32_bf16 v[22:25], v[124:127], v[150:153], v[22:25]
	v_mfma_f32_16x16x32_bf16 v[18:21], v[124:127], v[154:157], v[18:21]
	s_nop 0
	s_nop 0
	v_lshl_add_u64 v[98:99], v[100:101], 0, s[10:11]
	v_lshl_add_u64 v[100:101], v[104:105], 0, s[16:17]
	v_lshl_add_u64 v[102:103], v[106:107], 0, s[10:11]
	v_lshl_add_u64 v[104:105], v[110:111], 0, s[16:17]
	v_lshl_add_u64 v[106:107], v[112:113], 0, s[10:11]
	v_cndmask_b32_e32 v99, v101, v99, vcc
	v_cndmask_b32_e32 v98, v100, v98, vcc
	v_cndmask_b32_e32 v103, v105, v103, vcc
	v_cndmask_b32_e32 v102, v104, v102, vcc
	v_cndmask_b32_e32 v107, v109, v107, vcc
	v_cndmask_b32_e32 v106, v108, v106, vcc
	s_waitcnt vmcnt(0)
	v_mfma_f32_16x16x32_bf16 v[14:17], v[138:141], v[142:145], v[14:17]
	s_nop 0
	v_mfma_f32_16x16x32_bf16 v[10:13], v[138:141], v[146:149], v[10:13]
	v_mfma_f32_16x16x32_bf16 v[6:9], v[138:141], v[150:153], v[6:9]
	v_mfma_f32_16x16x32_bf16 v[2:5], v[138:141], v[154:157], v[2:5]
	v_mfma_f32_16x16x32_bf16 v[62:65], v[184:187], v[174:177], v[62:65]
	v_mfma_f32_16x16x32_bf16 v[58:61], v[184:187], v[168:171], v[58:61]
	v_mfma_f32_16x16x32_bf16 v[54:57], v[184:187], v[180:183], v[54:57]
	v_mfma_f32_16x16x32_bf16 v[50:53], v[184:187], v[218:221], v[50:53]
	v_mfma_f32_16x16x32_bf16 v[46:49], v[188:191], v[174:177], v[46:49]
	v_mfma_f32_16x16x32_bf16 v[42:45], v[188:191], v[168:171], v[42:45]
	v_mfma_f32_16x16x32_bf16 v[38:41], v[188:191], v[180:183], v[38:41]
	v_mfma_f32_16x16x32_bf16 v[34:37], v[188:191], v[218:221], v[34:37]
	v_mfma_f32_16x16x32_bf16 v[30:33], v[192:195], v[174:177], v[30:33]
	v_mfma_f32_16x16x32_bf16 v[26:29], v[192:195], v[168:171], v[26:29]
	v_mfma_f32_16x16x32_bf16 v[22:25], v[192:195], v[180:183], v[22:25]
	v_mfma_f32_16x16x32_bf16 v[18:21], v[192:195], v[218:221], v[18:21]
	v_mfma_f32_16x16x32_bf16 v[14:17], v[212:215], v[174:177], v[14:17]
	v_mfma_f32_16x16x32_bf16 v[10:13], v[212:215], v[168:171], v[10:13]
	v_mfma_f32_16x16x32_bf16 v[6:9], v[212:215], v[180:183], v[6:9]
	v_mfma_f32_16x16x32_bf16 v[2:5], v[212:215], v[218:221], v[2:5]
	v_add_u32_e32 v222, 0x80, v222
	s_cbranch_scc1 .LBB0_325
	v_ashrrev_i32_e32 v1, 4, v1
	v_and_b32_e32 v68, -4, v1
	s_mov_b32 s3, s89
	v_ashrrev_i32_e32 v69, 31, v68
	v_lshl_add_u64 v[70:71], s[2:3], 0, v[68:69]
	v_mul_f32_e32 v69, 0x3d372713, v62
	v_mul_f32_e32 v69, v62, v69
	v_fma_f32 v69, v62, v69, v62
	v_mul_f32_e32 v69, 0x3f4c422a, v69
	v_mul_f32_e32 v69, -2.0, v69
	v_mul_f32_e32 v69, 0x3fb8aa3b, v69
	v_exp_f32_e32 v72, v69
	v_mul_f32_e32 v69, 0x3d372713, v63
	v_mul_f32_e32 v69, v63, v69
	v_fma_f32 v69, v63, v69, v63
	v_mul_f32_e32 v69, 0x3f4c422a, v69
	v_mul_f32_e32 v69, -2.0, v69
	v_mul_f32_e32 v69, 0x3fb8aa3b, v69
	v_exp_f32_e32 v73, v69
	v_lshlrev_b32_e32 v66, 3, v119
	v_readlane_b32 s0, v253, 57
	v_and_b32_e32 v130, 24, v66
	v_pk_add_f32 v[72:73], v[72:73], 1.0 op_sel_hi:[1,0]
	v_readlane_b32 s1, v253, 58
	v_div_scale_f32 v69, s[4:5], v73, v73, v63
	v_rcp_f32_e32 v74, v69
	v_lshl_add_u64 v[66:67], s[0:1], 0, v[130:131]
	v_or_b32_e32 v130, s6, v118
	v_fma_f32 v75, -v69, v74, 1.0
	v_fmac_f32_e32 v74, v75, v74
	v_div_scale_f32 v75, vcc, v63, v73, v63
	v_mul_f32_e32 v76, v75, v74
	v_fma_f32 v77, -v69, v76, v75
	v_fmac_f32_e32 v76, v77, v74
	v_fma_f32 v69, -v69, v76, v75
	v_div_fmas_f32 v69, v69, v74, v76
	v_div_fixup_f32 v63, v69, v73, v63
	v_div_scale_f32 v69, s[4:5], v72, v72, v62
	v_rcp_f32_e32 v73, v69
	s_barrier
	v_fma_f32 v74, -v69, v73, 1.0
	v_fmac_f32_e32 v73, v74, v73
	v_div_scale_f32 v74, vcc, v62, v72, v62
	v_mul_f32_e32 v75, v74, v73
	v_fma_f32 v76, -v69, v75, v74
	v_fmac_f32_e32 v75, v76, v73
	v_fma_f32 v69, -v69, v75, v74
	v_div_fmas_f32 v69, v69, v73, v75
	v_div_fixup_f32 v62, v69, v72, v62
	v_cvt_pk_bf16_f32 v62, v62, v63
	v_mul_f32_e32 v63, 0x3d372713, v64
	v_mul_f32_e32 v63, v64, v63
	v_fma_f32 v63, v64, v63, v64
	v_mul_f32_e32 v63, 0x3f4c422a, v63
	v_mul_f32_e32 v63, -2.0, v63
	v_mul_f32_e32 v63, 0x3fb8aa3b, v63
	v_exp_f32_e32 v72, v63
	v_mul_f32_e32 v63, 0x3d372713, v65
	v_mul_f32_e32 v63, v65, v63
	v_fma_f32 v63, v65, v63, v65
	v_mul_f32_e32 v63, 0x3f4c422a, v63
	v_mul_f32_e32 v63, -2.0, v63
	v_mul_f32_e32 v63, 0x3fb8aa3b, v63
	v_exp_f32_e32 v73, v63
	s_nop 0
	v_pk_add_f32 v[72:73], v[72:73], 1.0 op_sel_hi:[1,0]
	s_nop 0
	v_div_scale_f32 v63, s[4:5], v73, v73, v65
	v_rcp_f32_e32 v69, v63
	s_nop 0
	v_fma_f32 v74, -v63, v69, 1.0
	v_fmac_f32_e32 v69, v74, v69
	v_div_scale_f32 v74, vcc, v65, v73, v65
	v_mul_f32_e32 v75, v74, v69
	v_fma_f32 v76, -v63, v75, v74
	v_fmac_f32_e32 v75, v76, v69
	v_fma_f32 v63, -v63, v75, v74
	v_div_fmas_f32 v63, v63, v69, v75
	v_div_fixup_f32 v63, v63, v73, v65
	v_div_scale_f32 v65, s[4:5], v72, v72, v64
	v_rcp_f32_e32 v69, v65
	s_nop 0
	v_fma_f32 v73, -v65, v69, 1.0
	v_fmac_f32_e32 v69, v73, v69
	v_div_scale_f32 v73, vcc, v64, v72, v64
	v_mul_f32_e32 v74, v73, v69
	v_fma_f32 v75, -v65, v74, v73
	v_fmac_f32_e32 v74, v75, v69
	v_fma_f32 v65, -v65, v74, v73
	v_div_fmas_f32 v65, v65, v69, v74
	v_div_fixup_f32 v64, v65, v72, v64
	v_cvt_pk_bf16_f32 v63, v64, v63
	v_lshl_add_u64 v[64:65], v[70:71], 0, v[130:131]
	v_lshlrev_b64 v[64:65], 5, v[64:65]
	v_lshl_add_u64 v[64:65], v[66:67], 0, v[64:65]
	global_store_dwordx2 v[64:65], v[62:63], off
	v_mul_f32_e32 v62, 0x3d372713, v58
	v_mul_f32_e32 v63, 0x3d372713, v59
	v_mul_f32_e32 v62, v58, v62
	v_mul_f32_e32 v63, v59, v63
	v_fma_f32 v62, v58, v62, v58
	v_fma_f32 v63, v59, v63, v59
	v_mul_f32_e32 v62, 0x3f4c422a, v62
	v_mul_f32_e32 v63, 0x3f4c422a, v63
	v_mul_f32_e32 v62, -2.0, v62
	v_mul_f32_e32 v63, -2.0, v63
	v_mul_f32_e32 v62, 0x3fb8aa3b, v62
	v_mul_f32_e32 v63, 0x3fb8aa3b, v63
	v_exp_f32_e32 v62, v62
	v_exp_f32_e32 v63, v63
	s_nop 0
	v_pk_add_f32 v[62:63], v[62:63], 1.0 op_sel_hi:[1,0]
	s_nop 0
	v_div_scale_f32 v64, s[4:5], v63, v63, v59
	v_rcp_f32_e32 v65, v64
	s_nop 0
	v_fma_f32 v69, -v64, v65, 1.0
	v_fmac_f32_e32 v65, v69, v65
	v_div_scale_f32 v69, vcc, v59, v63, v59
	v_mul_f32_e32 v72, v69, v65
	v_fma_f32 v73, -v64, v72, v69
	v_fmac_f32_e32 v72, v73, v65
	v_fma_f32 v64, -v64, v72, v69
	v_div_fmas_f32 v64, v64, v65, v72
	v_div_fixup_f32 v59, v64, v63, v59
	v_div_scale_f32 v63, s[4:5], v62, v62, v58
	v_rcp_f32_e32 v64, v63
	s_nop 0
	v_fma_f32 v65, -v63, v64, 1.0
	v_fmac_f32_e32 v64, v65, v64
	v_div_scale_f32 v65, vcc, v58, v62, v58
	v_mul_f32_e32 v69, v65, v64
	v_fma_f32 v72, -v63, v69, v65
	v_fmac_f32_e32 v69, v72, v64
	v_fma_f32 v63, -v63, v69, v65
	v_div_fmas_f32 v63, v63, v64, v69
	v_div_fixup_f32 v58, v63, v62, v58
	v_cvt_pk_bf16_f32 v62, v58, v59
	v_mul_f32_e32 v58, 0x3d372713, v60
	v_mul_f32_e32 v59, 0x3d372713, v61
	v_mul_f32_e32 v58, v60, v58
	v_mul_f32_e32 v59, v61, v59
	v_fma_f32 v58, v60, v58, v60
	v_fma_f32 v59, v61, v59, v61
	v_mul_f32_e32 v58, 0x3f4c422a, v58
	v_mul_f32_e32 v59, 0x3f4c422a, v59
	v_mul_f32_e32 v58, -2.0, v58
	v_mul_f32_e32 v59, -2.0, v59
	v_mul_f32_e32 v58, 0x3fb8aa3b, v58
	v_mul_f32_e32 v59, 0x3fb8aa3b, v59
	v_exp_f32_e32 v58, v58
	v_exp_f32_e32 v59, v59
	s_nop 0
	v_pk_add_f32 v[58:59], v[58:59], 1.0 op_sel_hi:[1,0]
	s_nop 0
	v_div_scale_f32 v63, s[4:5], v59, v59, v61
	v_rcp_f32_e32 v64, v63
	s_nop 0
	v_fma_f32 v65, -v63, v64, 1.0
	v_fmac_f32_e32 v64, v65, v64
	v_div_scale_f32 v65, vcc, v61, v59, v61
	v_mul_f32_e32 v69, v65, v64
	v_fma_f32 v72, -v63, v69, v65
	v_fmac_f32_e32 v69, v72, v64
	v_fma_f32 v63, -v63, v69, v65
	v_div_fmas_f32 v63, v63, v64, v69
	v_div_fixup_f32 v59, v63, v59, v61
	v_div_scale_f32 v61, s[4:5], v58, v58, v60
	v_rcp_f32_e32 v63, v61
	s_nop 0
	v_fma_f32 v64, -v61, v63, 1.0
	v_fmac_f32_e32 v63, v64, v63
	v_div_scale_f32 v64, vcc, v60, v58, v60
	v_mul_f32_e32 v65, v64, v63
	v_fma_f32 v69, -v61, v65, v64
	v_fmac_f32_e32 v65, v69, v63
	v_fma_f32 v61, -v61, v65, v64
	v_div_fmas_f32 v61, v61, v63, v65
	v_div_fixup_f32 v58, v61, v58, v60
	v_cvt_pk_bf16_f32 v63, v58, v59
	v_or_b32_e32 v58, 0x100, v130
	v_mov_b32_e32 v59, v131
	v_lshl_add_u64 v[60:61], v[70:71], 0, v[58:59]
	v_lshlrev_b64 v[60:61], 5, v[60:61]
	v_lshl_add_u64 v[60:61], v[66:67], 0, v[60:61]
	global_store_dwordx2 v[60:61], v[62:63], off
	v_mul_f32_e32 v60, 0x3d372713, v54
	v_mul_f32_e32 v61, 0x3d372713, v55
	v_mul_f32_e32 v60, v54, v60
	v_mul_f32_e32 v61, v55, v61
	v_fma_f32 v60, v54, v60, v54
	v_fma_f32 v61, v55, v61, v55
	v_mul_f32_e32 v60, 0x3f4c422a, v60
	v_mul_f32_e32 v61, 0x3f4c422a, v61
	v_mul_f32_e32 v60, -2.0, v60
	v_mul_f32_e32 v61, -2.0, v61
	v_mul_f32_e32 v60, 0x3fb8aa3b, v60
	v_mul_f32_e32 v61, 0x3fb8aa3b, v61
	v_exp_f32_e32 v60, v60
	v_exp_f32_e32 v61, v61
	s_nop 0
	v_pk_add_f32 v[60:61], v[60:61], 1.0 op_sel_hi:[1,0]
	s_nop 0
	v_div_scale_f32 v62, s[4:5], v61, v61, v55
	v_rcp_f32_e32 v63, v62
	s_nop 0
	v_fma_f32 v64, -v62, v63, 1.0
	v_fmac_f32_e32 v63, v64, v63
	v_div_scale_f32 v64, vcc, v55, v61, v55
	v_mul_f32_e32 v65, v64, v63
	v_fma_f32 v69, -v62, v65, v64
	v_fmac_f32_e32 v65, v69, v63
	v_fma_f32 v62, -v62, v65, v64
	v_div_fmas_f32 v62, v62, v63, v65
	v_div_fixup_f32 v55, v62, v61, v55
	v_div_scale_f32 v61, s[4:5], v60, v60, v54
	v_rcp_f32_e32 v62, v61
	s_nop 0
	v_fma_f32 v63, -v61, v62, 1.0
	v_fmac_f32_e32 v62, v63, v62
	v_div_scale_f32 v63, vcc, v54, v60, v54
	v_mul_f32_e32 v64, v63, v62
	v_fma_f32 v65, -v61, v64, v63
	v_fmac_f32_e32 v64, v65, v62
	v_fma_f32 v61, -v61, v64, v63
	v_div_fmas_f32 v61, v61, v62, v64
	v_div_fixup_f32 v54, v61, v60, v54
	v_cvt_pk_bf16_f32 v60, v54, v55
	v_mul_f32_e32 v54, 0x3d372713, v56
	v_mul_f32_e32 v55, 0x3d372713, v57
	v_mul_f32_e32 v54, v56, v54
	v_mul_f32_e32 v55, v57, v55
	v_fma_f32 v54, v56, v54, v56
	v_fma_f32 v55, v57, v55, v57
	v_mul_f32_e32 v54, 0x3f4c422a, v54
	v_mul_f32_e32 v55, 0x3f4c422a, v55
	v_mul_f32_e32 v54, -2.0, v54
	v_mul_f32_e32 v55, -2.0, v55
	v_mul_f32_e32 v54, 0x3fb8aa3b, v54
	v_mul_f32_e32 v55, 0x3fb8aa3b, v55
	v_exp_f32_e32 v54, v54
	v_exp_f32_e32 v55, v55
	s_nop 0
	v_pk_add_f32 v[54:55], v[54:55], 1.0 op_sel_hi:[1,0]
	s_nop 0
	v_div_scale_f32 v61, s[4:5], v55, v55, v57
	v_rcp_f32_e32 v62, v61
	s_nop 0
	v_fma_f32 v63, -v61, v62, 1.0
	v_fmac_f32_e32 v62, v63, v62
	v_div_scale_f32 v63, vcc, v57, v55, v57
	v_mul_f32_e32 v64, v63, v62
	v_fma_f32 v65, -v61, v64, v63
	v_fmac_f32_e32 v64, v65, v62
	v_fma_f32 v61, -v61, v64, v63
	v_div_fmas_f32 v61, v61, v62, v64
	v_div_fixup_f32 v55, v61, v55, v57
	v_div_scale_f32 v57, s[4:5], v54, v54, v56
	v_rcp_f32_e32 v61, v57
	s_nop 0
	v_fma_f32 v62, -v57, v61, 1.0
	v_fmac_f32_e32 v61, v62, v61
	v_div_scale_f32 v62, vcc, v56, v54, v56
	v_mul_f32_e32 v63, v62, v61
	v_fma_f32 v64, -v57, v63, v62
	v_fmac_f32_e32 v63, v64, v61
	v_fma_f32 v57, -v57, v63, v62
	v_div_fmas_f32 v57, v57, v61, v63
	v_div_fixup_f32 v54, v57, v54, v56
	v_cvt_pk_bf16_f32 v61, v54, v55
	v_or_b32_e32 v54, 0x200, v130
	v_mov_b32_e32 v55, v131
	v_lshl_add_u64 v[56:57], v[70:71], 0, v[54:55]
	v_lshlrev_b64 v[56:57], 5, v[56:57]
	v_lshl_add_u64 v[56:57], v[66:67], 0, v[56:57]
	global_store_dwordx2 v[56:57], v[60:61], off
	v_mul_f32_e32 v56, 0x3d372713, v50
	v_mul_f32_e32 v57, 0x3d372713, v51
	v_mul_f32_e32 v56, v50, v56
	v_mul_f32_e32 v57, v51, v57
	v_fma_f32 v56, v50, v56, v50
	v_fma_f32 v57, v51, v57, v51
	v_mul_f32_e32 v56, 0x3f4c422a, v56
	v_mul_f32_e32 v57, 0x3f4c422a, v57
	v_mul_f32_e32 v56, -2.0, v56
	v_mul_f32_e32 v57, -2.0, v57
	v_mul_f32_e32 v56, 0x3fb8aa3b, v56
	v_mul_f32_e32 v57, 0x3fb8aa3b, v57
	v_exp_f32_e32 v56, v56
	v_exp_f32_e32 v57, v57
	s_nop 0
	v_pk_add_f32 v[56:57], v[56:57], 1.0 op_sel_hi:[1,0]
	s_nop 0
	v_div_scale_f32 v60, s[4:5], v57, v57, v51
	v_rcp_f32_e32 v61, v60
	s_nop 0
	v_fma_f32 v62, -v60, v61, 1.0
	v_fmac_f32_e32 v61, v62, v61
	v_div_scale_f32 v62, vcc, v51, v57, v51
	v_mul_f32_e32 v63, v62, v61
	v_fma_f32 v64, -v60, v63, v62
	v_fmac_f32_e32 v63, v64, v61
	v_fma_f32 v60, -v60, v63, v62
	v_div_fmas_f32 v60, v60, v61, v63
	v_div_fixup_f32 v51, v60, v57, v51
	v_div_scale_f32 v57, s[4:5], v56, v56, v50
	v_rcp_f32_e32 v60, v57
	s_nop 0
	v_fma_f32 v61, -v57, v60, 1.0
	v_fmac_f32_e32 v60, v61, v60
	v_div_scale_f32 v61, vcc, v50, v56, v50
	v_mul_f32_e32 v62, v61, v60
	v_fma_f32 v63, -v57, v62, v61
	v_fmac_f32_e32 v62, v63, v60
	v_fma_f32 v57, -v57, v62, v61
	v_div_fmas_f32 v57, v57, v60, v62
	v_div_fixup_f32 v50, v57, v56, v50
	v_cvt_pk_bf16_f32 v56, v50, v51
	v_mul_f32_e32 v50, 0x3d372713, v52
	v_mul_f32_e32 v51, 0x3d372713, v53
	v_mul_f32_e32 v50, v52, v50
	v_mul_f32_e32 v51, v53, v51
	v_fma_f32 v50, v52, v50, v52
	v_fma_f32 v51, v53, v51, v53
	v_mul_f32_e32 v50, 0x3f4c422a, v50
	v_mul_f32_e32 v51, 0x3f4c422a, v51
	v_mul_f32_e32 v50, -2.0, v50
	v_mul_f32_e32 v51, -2.0, v51
	v_mul_f32_e32 v50, 0x3fb8aa3b, v50
	v_mul_f32_e32 v51, 0x3fb8aa3b, v51
	v_exp_f32_e32 v50, v50
	v_exp_f32_e32 v51, v51
	s_nop 0
	v_pk_add_f32 v[50:51], v[50:51], 1.0 op_sel_hi:[1,0]
	s_nop 0
	v_div_scale_f32 v57, s[4:5], v51, v51, v53
	v_rcp_f32_e32 v60, v57
	s_nop 0
	v_fma_f32 v61, -v57, v60, 1.0
	v_fmac_f32_e32 v60, v61, v60
	v_div_scale_f32 v61, vcc, v53, v51, v53
	v_mul_f32_e32 v62, v61, v60
	v_fma_f32 v63, -v57, v62, v61
	v_fmac_f32_e32 v62, v63, v60
	v_fma_f32 v57, -v57, v62, v61
	v_div_fmas_f32 v57, v57, v60, v62
	v_div_fixup_f32 v51, v57, v51, v53
	v_div_scale_f32 v53, s[4:5], v50, v50, v52
	v_rcp_f32_e32 v57, v53
	s_nop 0
	v_fma_f32 v60, -v53, v57, 1.0
	v_fmac_f32_e32 v57, v60, v57
	v_div_scale_f32 v60, vcc, v52, v50, v52
	v_mul_f32_e32 v61, v60, v57
	v_fma_f32 v62, -v53, v61, v60
	v_fmac_f32_e32 v61, v62, v57
	v_fma_f32 v53, -v53, v61, v60
	v_div_fmas_f32 v53, v53, v57, v61
	v_div_fixup_f32 v50, v53, v50, v52
	v_cvt_pk_bf16_f32 v57, v50, v51
	v_or_b32_e32 v50, 0x300, v130
	v_mov_b32_e32 v51, v131
	v_lshl_add_u64 v[52:53], v[70:71], 0, v[50:51]
	v_lshlrev_b64 v[52:53], 5, v[52:53]
	v_lshl_add_u64 v[52:53], v[66:67], 0, v[52:53]
	global_store_dwordx2 v[52:53], v[56:57], off
	v_mul_f32_e32 v56, 0x3d372713, v46
	v_mul_f32_e32 v57, 0x3d372713, v47
	v_mul_f32_e32 v56, v46, v56
	v_mul_f32_e32 v57, v47, v57
	v_fma_f32 v56, v46, v56, v46
	v_fma_f32 v57, v47, v57, v47
	v_mul_f32_e32 v56, 0x3f4c422a, v56
	v_mul_f32_e32 v57, 0x3f4c422a, v57
	v_mul_f32_e32 v56, -2.0, v56
	v_mul_f32_e32 v57, -2.0, v57
	v_mul_f32_e32 v56, 0x3fb8aa3b, v56
	v_mul_f32_e32 v57, 0x3fb8aa3b, v57
	v_exp_f32_e32 v56, v56
	v_exp_f32_e32 v57, v57
	v_or_b32_e32 v52, 1, v68
	v_ashrrev_i32_e32 v53, 31, v52
	v_lshl_add_u64 v[52:53], s[2:3], 0, v[52:53]
	v_pk_add_f32 v[56:57], v[56:57], 1.0 op_sel_hi:[1,0]
	s_nop 0
	v_div_scale_f32 v60, s[4:5], v57, v57, v47
	v_rcp_f32_e32 v61, v60
	s_nop 0
	v_fma_f32 v62, -v60, v61, 1.0
	v_fmac_f32_e32 v61, v62, v61
	v_div_scale_f32 v62, vcc, v47, v57, v47
	v_mul_f32_e32 v63, v62, v61
	v_fma_f32 v64, -v60, v63, v62
	v_fmac_f32_e32 v63, v64, v61
	v_fma_f32 v60, -v60, v63, v62
	v_div_fmas_f32 v60, v60, v61, v63
	v_div_fixup_f32 v47, v60, v57, v47
	v_div_scale_f32 v57, s[4:5], v56, v56, v46
	v_rcp_f32_e32 v60, v57
	s_nop 0
	v_fma_f32 v61, -v57, v60, 1.0
	v_fmac_f32_e32 v60, v61, v60
	v_div_scale_f32 v61, vcc, v46, v56, v46
	v_mul_f32_e32 v62, v61, v60
	v_fma_f32 v63, -v57, v62, v61
	v_fmac_f32_e32 v62, v63, v60
	v_fma_f32 v57, -v57, v62, v61
	v_div_fmas_f32 v57, v57, v60, v62
	v_div_fixup_f32 v46, v57, v56, v46
	v_cvt_pk_bf16_f32 v46, v46, v47
	v_mul_f32_e32 v47, 0x3d372713, v48
	v_mul_f32_e32 v47, v48, v47
	v_fma_f32 v47, v48, v47, v48
	v_mul_f32_e32 v47, 0x3f4c422a, v47
	v_mul_f32_e32 v47, -2.0, v47
	v_mul_f32_e32 v47, 0x3fb8aa3b, v47
	v_exp_f32_e32 v56, v47
	v_mul_f32_e32 v47, 0x3d372713, v49
	v_mul_f32_e32 v47, v49, v47
	v_fma_f32 v47, v49, v47, v49
	v_mul_f32_e32 v47, 0x3f4c422a, v47
	v_mul_f32_e32 v47, -2.0, v47
	v_mul_f32_e32 v47, 0x3fb8aa3b, v47
	v_exp_f32_e32 v57, v47
	s_nop 0
	v_pk_add_f32 v[56:57], v[56:57], 1.0 op_sel_hi:[1,0]
	s_nop 0
	v_div_scale_f32 v47, s[4:5], v57, v57, v49
	v_rcp_f32_e32 v60, v47
	s_nop 0
	v_fma_f32 v61, -v47, v60, 1.0
	v_fmac_f32_e32 v60, v61, v60
	v_div_scale_f32 v61, vcc, v49, v57, v49
	v_mul_f32_e32 v62, v61, v60
	v_fma_f32 v63, -v47, v62, v61
	v_fmac_f32_e32 v62, v63, v60
	v_fma_f32 v47, -v47, v62, v61
	v_div_fmas_f32 v47, v47, v60, v62
	v_div_fixup_f32 v47, v47, v57, v49
	v_div_scale_f32 v49, s[4:5], v56, v56, v48
	v_rcp_f32_e32 v57, v49
	s_nop 0
	v_fma_f32 v60, -v49, v57, 1.0
	v_fmac_f32_e32 v57, v60, v57
	v_div_scale_f32 v60, vcc, v48, v56, v48
	v_mul_f32_e32 v61, v60, v57
	v_fma_f32 v62, -v49, v61, v60
	v_fmac_f32_e32 v61, v62, v57
	v_fma_f32 v49, -v49, v61, v60
	v_div_fmas_f32 v49, v49, v57, v61
	v_div_fixup_f32 v48, v49, v56, v48
	v_cvt_pk_bf16_f32 v47, v48, v47
	v_lshl_add_u64 v[48:49], v[52:53], 0, v[130:131]
	v_lshlrev_b64 v[48:49], 5, v[48:49]
	v_lshl_add_u64 v[48:49], v[66:67], 0, v[48:49]
	global_store_dwordx2 v[48:49], v[46:47], off
	v_mul_f32_e32 v46, 0x3d372713, v42
	v_mul_f32_e32 v47, 0x3d372713, v43
	v_mul_f32_e32 v46, v42, v46
	v_mul_f32_e32 v47, v43, v47
	v_fma_f32 v46, v42, v46, v42
	v_fma_f32 v47, v43, v47, v43
	v_mul_f32_e32 v46, 0x3f4c422a, v46
	v_mul_f32_e32 v47, 0x3f4c422a, v47
	v_mul_f32_e32 v46, -2.0, v46
	v_mul_f32_e32 v47, -2.0, v47
	v_mul_f32_e32 v46, 0x3fb8aa3b, v46
	v_mul_f32_e32 v47, 0x3fb8aa3b, v47
	v_exp_f32_e32 v46, v46
	v_exp_f32_e32 v47, v47
	s_nop 0
	v_pk_add_f32 v[46:47], v[46:47], 1.0 op_sel_hi:[1,0]
	s_nop 0
	v_div_scale_f32 v48, s[4:5], v47, v47, v43
	v_rcp_f32_e32 v49, v48
	s_nop 0
	v_fma_f32 v56, -v48, v49, 1.0
	v_fmac_f32_e32 v49, v56, v49
	v_div_scale_f32 v56, vcc, v43, v47, v43
	v_mul_f32_e32 v57, v56, v49
	v_fma_f32 v60, -v48, v57, v56
	v_fmac_f32_e32 v57, v60, v49
	v_fma_f32 v48, -v48, v57, v56
	v_div_fmas_f32 v48, v48, v49, v57
	v_div_fixup_f32 v43, v48, v47, v43
	v_div_scale_f32 v47, s[4:5], v46, v46, v42
	v_rcp_f32_e32 v48, v47
	s_nop 0
	v_fma_f32 v49, -v47, v48, 1.0
	v_fmac_f32_e32 v48, v49, v48
	v_div_scale_f32 v49, vcc, v42, v46, v42
	v_mul_f32_e32 v56, v49, v48
	v_fma_f32 v57, -v47, v56, v49
	v_fmac_f32_e32 v56, v57, v48
	v_fma_f32 v47, -v47, v56, v49
	v_div_fmas_f32 v47, v47, v48, v56
	v_div_fixup_f32 v42, v47, v46, v42
	v_cvt_pk_bf16_f32 v42, v42, v43
	v_mul_f32_e32 v43, 0x3d372713, v44
	v_mul_f32_e32 v43, v44, v43
	v_fma_f32 v43, v44, v43, v44
	v_mul_f32_e32 v43, 0x3f4c422a, v43
	v_mul_f32_e32 v43, -2.0, v43
	v_mul_f32_e32 v43, 0x3fb8aa3b, v43
	v_exp_f32_e32 v46, v43
	v_mul_f32_e32 v43, 0x3d372713, v45
	v_mul_f32_e32 v43, v45, v43
	v_fma_f32 v43, v45, v43, v45
	v_mul_f32_e32 v43, 0x3f4c422a, v43
	v_mul_f32_e32 v43, -2.0, v43
	v_mul_f32_e32 v43, 0x3fb8aa3b, v43
	v_exp_f32_e32 v47, v43
	s_nop 0
	v_pk_add_f32 v[46:47], v[46:47], 1.0 op_sel_hi:[1,0]
	s_nop 0
	v_div_scale_f32 v43, s[4:5], v47, v47, v45
	v_rcp_f32_e32 v48, v43
	s_nop 0
	v_fma_f32 v49, -v43, v48, 1.0
	v_fmac_f32_e32 v48, v49, v48
	v_div_scale_f32 v49, vcc, v45, v47, v45
	v_mul_f32_e32 v56, v49, v48
	v_fma_f32 v57, -v43, v56, v49
	v_fmac_f32_e32 v56, v57, v48
	v_fma_f32 v43, -v43, v56, v49
	v_div_fmas_f32 v43, v43, v48, v56
	v_div_fixup_f32 v43, v43, v47, v45
	v_div_scale_f32 v45, s[4:5], v46, v46, v44
	v_rcp_f32_e32 v47, v45
	s_nop 0
	v_fma_f32 v48, -v45, v47, 1.0
	v_fmac_f32_e32 v47, v48, v47
	v_div_scale_f32 v48, vcc, v44, v46, v44
	v_mul_f32_e32 v49, v48, v47
	v_fma_f32 v56, -v45, v49, v48
	v_fmac_f32_e32 v49, v56, v47
	v_fma_f32 v45, -v45, v49, v48
	v_div_fmas_f32 v45, v45, v47, v49
	v_div_fixup_f32 v44, v45, v46, v44
	v_cvt_pk_bf16_f32 v43, v44, v43
	v_lshl_add_u64 v[44:45], v[52:53], 0, v[58:59]
	v_lshlrev_b64 v[44:45], 5, v[44:45]
	v_lshl_add_u64 v[44:45], v[66:67], 0, v[44:45]
	global_store_dwordx2 v[44:45], v[42:43], off
	v_mul_f32_e32 v42, 0x3d372713, v38
	v_mul_f32_e32 v43, 0x3d372713, v39
	v_mul_f32_e32 v42, v38, v42
	v_mul_f32_e32 v43, v39, v43
	v_fma_f32 v42, v38, v42, v38
	v_fma_f32 v43, v39, v43, v39
	v_mul_f32_e32 v42, 0x3f4c422a, v42
	v_mul_f32_e32 v43, 0x3f4c422a, v43
	v_mul_f32_e32 v42, -2.0, v42
	v_mul_f32_e32 v43, -2.0, v43
	v_mul_f32_e32 v42, 0x3fb8aa3b, v42
	v_mul_f32_e32 v43, 0x3fb8aa3b, v43
	v_exp_f32_e32 v42, v42
	v_exp_f32_e32 v43, v43
	s_nop 0
	v_pk_add_f32 v[42:43], v[42:43], 1.0 op_sel_hi:[1,0]
	s_nop 0
	v_div_scale_f32 v44, s[4:5], v43, v43, v39
	v_rcp_f32_e32 v45, v44
	s_nop 0
	v_fma_f32 v46, -v44, v45, 1.0
	v_fmac_f32_e32 v45, v46, v45
	v_div_scale_f32 v46, vcc, v39, v43, v39
	v_mul_f32_e32 v47, v46, v45
	v_fma_f32 v48, -v44, v47, v46
	v_fmac_f32_e32 v47, v48, v45
	v_fma_f32 v44, -v44, v47, v46
	v_div_fmas_f32 v44, v44, v45, v47
	v_div_fixup_f32 v39, v44, v43, v39
	v_div_scale_f32 v43, s[4:5], v42, v42, v38
	v_rcp_f32_e32 v44, v43
	s_nop 0
	v_fma_f32 v45, -v43, v44, 1.0
	v_fmac_f32_e32 v44, v45, v44
	v_div_scale_f32 v45, vcc, v38, v42, v38
	v_mul_f32_e32 v46, v45, v44
	v_fma_f32 v47, -v43, v46, v45
	v_fmac_f32_e32 v46, v47, v44
	v_fma_f32 v43, -v43, v46, v45
	v_div_fmas_f32 v43, v43, v44, v46
	v_div_fixup_f32 v38, v43, v42, v38
	v_cvt_pk_bf16_f32 v38, v38, v39
	v_mul_f32_e32 v39, 0x3d372713, v40
	v_mul_f32_e32 v39, v40, v39
	v_fma_f32 v39, v40, v39, v40
	v_mul_f32_e32 v39, 0x3f4c422a, v39
	v_mul_f32_e32 v39, -2.0, v39
	v_mul_f32_e32 v39, 0x3fb8aa3b, v39
	v_exp_f32_e32 v42, v39
	v_mul_f32_e32 v39, 0x3d372713, v41
	v_mul_f32_e32 v39, v41, v39
	v_fma_f32 v39, v41, v39, v41
	v_mul_f32_e32 v39, 0x3f4c422a, v39
	v_mul_f32_e32 v39, -2.0, v39
	v_mul_f32_e32 v39, 0x3fb8aa3b, v39
	v_exp_f32_e32 v43, v39
	s_nop 0
	v_pk_add_f32 v[42:43], v[42:43], 1.0 op_sel_hi:[1,0]
	s_nop 0
	v_div_scale_f32 v39, s[4:5], v43, v43, v41
	v_rcp_f32_e32 v44, v39
	s_nop 0
	v_fma_f32 v45, -v39, v44, 1.0
	v_fmac_f32_e32 v44, v45, v44
	v_div_scale_f32 v45, vcc, v41, v43, v41
	v_mul_f32_e32 v46, v45, v44
	v_fma_f32 v47, -v39, v46, v45
	v_fmac_f32_e32 v46, v47, v44
	v_fma_f32 v39, -v39, v46, v45
	v_div_fmas_f32 v39, v39, v44, v46
	v_div_fixup_f32 v39, v39, v43, v41
	v_div_scale_f32 v41, s[4:5], v42, v42, v40
	v_rcp_f32_e32 v43, v41
	s_nop 0
	v_fma_f32 v44, -v41, v43, 1.0
	v_fmac_f32_e32 v43, v44, v43
	v_div_scale_f32 v44, vcc, v40, v42, v40
	v_mul_f32_e32 v45, v44, v43
	v_fma_f32 v46, -v41, v45, v44
	v_fmac_f32_e32 v45, v46, v43
	v_fma_f32 v41, -v41, v45, v44
	v_div_fmas_f32 v41, v41, v43, v45
	v_div_fixup_f32 v40, v41, v42, v40
	v_cvt_pk_bf16_f32 v39, v40, v39
	v_lshl_add_u64 v[40:41], v[52:53], 0, v[54:55]
	v_lshlrev_b64 v[40:41], 5, v[40:41]
	v_lshl_add_u64 v[40:41], v[66:67], 0, v[40:41]
	global_store_dwordx2 v[40:41], v[38:39], off
	v_mul_f32_e32 v38, 0x3d372713, v34
	v_mul_f32_e32 v39, 0x3d372713, v35
	v_mul_f32_e32 v38, v34, v38
	v_mul_f32_e32 v39, v35, v39
	v_fma_f32 v38, v34, v38, v34
	v_fma_f32 v39, v35, v39, v35
	v_mul_f32_e32 v38, 0x3f4c422a, v38
	v_mul_f32_e32 v39, 0x3f4c422a, v39
	v_mul_f32_e32 v38, -2.0, v38
	v_mul_f32_e32 v39, -2.0, v39
	v_mul_f32_e32 v38, 0x3fb8aa3b, v38
	v_mul_f32_e32 v39, 0x3fb8aa3b, v39
	v_exp_f32_e32 v38, v38
	v_exp_f32_e32 v39, v39
	s_nop 0
	v_pk_add_f32 v[38:39], v[38:39], 1.0 op_sel_hi:[1,0]
	s_nop 0
	v_div_scale_f32 v40, s[4:5], v39, v39, v35
	v_rcp_f32_e32 v41, v40
	s_nop 0
	v_fma_f32 v42, -v40, v41, 1.0
	v_fmac_f32_e32 v41, v42, v41
	v_div_scale_f32 v42, vcc, v35, v39, v35
	v_mul_f32_e32 v43, v42, v41
	v_fma_f32 v44, -v40, v43, v42
	v_fmac_f32_e32 v43, v44, v41
	v_fma_f32 v40, -v40, v43, v42
	v_div_fmas_f32 v40, v40, v41, v43
	v_div_fixup_f32 v35, v40, v39, v35
	v_div_scale_f32 v39, s[4:5], v38, v38, v34
	v_rcp_f32_e32 v40, v39
	s_nop 0
	v_fma_f32 v41, -v39, v40, 1.0
	v_fmac_f32_e32 v40, v41, v40
	v_div_scale_f32 v41, vcc, v34, v38, v34
	v_mul_f32_e32 v42, v41, v40
	v_fma_f32 v43, -v39, v42, v41
	v_fmac_f32_e32 v42, v43, v40
	v_fma_f32 v39, -v39, v42, v41
	v_div_fmas_f32 v39, v39, v40, v42
	v_div_fixup_f32 v34, v39, v38, v34
	v_cvt_pk_bf16_f32 v34, v34, v35
	v_mul_f32_e32 v35, 0x3d372713, v36
	v_mul_f32_e32 v35, v36, v35
	v_fma_f32 v35, v36, v35, v36
	v_mul_f32_e32 v35, 0x3f4c422a, v35
	v_mul_f32_e32 v35, -2.0, v35
	v_mul_f32_e32 v35, 0x3fb8aa3b, v35
	v_exp_f32_e32 v38, v35
	v_mul_f32_e32 v35, 0x3d372713, v37
	v_mul_f32_e32 v35, v37, v35
	v_fma_f32 v35, v37, v35, v37
	v_mul_f32_e32 v35, 0x3f4c422a, v35
	v_mul_f32_e32 v35, -2.0, v35
	v_mul_f32_e32 v35, 0x3fb8aa3b, v35
	v_exp_f32_e32 v39, v35
	s_nop 0
	v_pk_add_f32 v[38:39], v[38:39], 1.0 op_sel_hi:[1,0]
	s_nop 0
	v_div_scale_f32 v35, s[4:5], v39, v39, v37
	v_rcp_f32_e32 v40, v35
	s_nop 0
	v_fma_f32 v41, -v35, v40, 1.0
	v_fmac_f32_e32 v40, v41, v40
	v_div_scale_f32 v41, vcc, v37, v39, v37
	v_mul_f32_e32 v42, v41, v40
	v_fma_f32 v43, -v35, v42, v41
	v_fmac_f32_e32 v42, v43, v40
	v_fma_f32 v35, -v35, v42, v41
	v_div_fmas_f32 v35, v35, v40, v42
	v_div_fixup_f32 v35, v35, v39, v37
	v_div_scale_f32 v37, s[4:5], v38, v38, v36
	v_rcp_f32_e32 v39, v37
	s_nop 0
	v_fma_f32 v40, -v37, v39, 1.0
	v_fmac_f32_e32 v39, v40, v39
	v_div_scale_f32 v40, vcc, v36, v38, v36
	v_mul_f32_e32 v41, v40, v39
	v_fma_f32 v42, -v37, v41, v40
	v_fmac_f32_e32 v41, v42, v39
	v_fma_f32 v37, -v37, v41, v40
	v_div_fmas_f32 v37, v37, v39, v41
	v_div_fixup_f32 v36, v37, v38, v36
	v_cvt_pk_bf16_f32 v35, v36, v35
	v_lshl_add_u64 v[36:37], v[52:53], 0, v[50:51]
	v_lshlrev_b64 v[36:37], 5, v[36:37]
	v_lshl_add_u64 v[36:37], v[66:67], 0, v[36:37]
	global_store_dwordx2 v[36:37], v[34:35], off
	v_mul_f32_e32 v36, 0x3d372713, v30
	v_mul_f32_e32 v37, 0x3d372713, v31
	v_mul_f32_e32 v36, v30, v36
	v_mul_f32_e32 v37, v31, v37
	v_fma_f32 v36, v30, v36, v30
	v_fma_f32 v37, v31, v37, v31
	v_mul_f32_e32 v36, 0x3f4c422a, v36
	v_mul_f32_e32 v37, 0x3f4c422a, v37
	v_mul_f32_e32 v36, -2.0, v36
	v_mul_f32_e32 v37, -2.0, v37
	v_mul_f32_e32 v36, 0x3fb8aa3b, v36
	v_mul_f32_e32 v37, 0x3fb8aa3b, v37
	v_exp_f32_e32 v36, v36
	v_exp_f32_e32 v37, v37
	v_or_b32_e32 v34, 2, v68
	v_ashrrev_i32_e32 v35, 31, v34
	v_lshl_add_u64 v[34:35], s[2:3], 0, v[34:35]
	v_pk_add_f32 v[36:37], v[36:37], 1.0 op_sel_hi:[1,0]
	s_nop 0
	v_div_scale_f32 v38, s[4:5], v37, v37, v31
	v_rcp_f32_e32 v39, v38
	s_nop 0
	v_fma_f32 v40, -v38, v39, 1.0
	v_fmac_f32_e32 v39, v40, v39
	v_div_scale_f32 v40, vcc, v31, v37, v31
	v_mul_f32_e32 v41, v40, v39
	v_fma_f32 v42, -v38, v41, v40
	v_fmac_f32_e32 v41, v42, v39
	v_fma_f32 v38, -v38, v41, v40
	v_div_fmas_f32 v38, v38, v39, v41
	v_div_fixup_f32 v31, v38, v37, v31
	v_div_scale_f32 v37, s[4:5], v36, v36, v30
	v_rcp_f32_e32 v38, v37
	s_nop 0
	v_fma_f32 v39, -v37, v38, 1.0
	v_fmac_f32_e32 v38, v39, v38
	v_div_scale_f32 v39, vcc, v30, v36, v30
	v_mul_f32_e32 v40, v39, v38
	v_fma_f32 v41, -v37, v40, v39
	v_fmac_f32_e32 v40, v41, v38
	v_fma_f32 v37, -v37, v40, v39
	v_div_fmas_f32 v37, v37, v38, v40
	v_div_fixup_f32 v30, v37, v36, v30
	v_cvt_pk_bf16_f32 v30, v30, v31
	v_mul_f32_e32 v31, 0x3d372713, v32
	v_mul_f32_e32 v31, v32, v31
	v_fma_f32 v31, v32, v31, v32
	v_mul_f32_e32 v31, 0x3f4c422a, v31
	v_mul_f32_e32 v31, -2.0, v31
	v_mul_f32_e32 v31, 0x3fb8aa3b, v31
	v_exp_f32_e32 v36, v31
	v_mul_f32_e32 v31, 0x3d372713, v33
	v_mul_f32_e32 v31, v33, v31
	v_fma_f32 v31, v33, v31, v33
	v_mul_f32_e32 v31, 0x3f4c422a, v31
	v_mul_f32_e32 v31, -2.0, v31
	v_mul_f32_e32 v31, 0x3fb8aa3b, v31
	v_exp_f32_e32 v37, v31
	s_nop 0
	v_pk_add_f32 v[36:37], v[36:37], 1.0 op_sel_hi:[1,0]
	s_nop 0
	v_div_scale_f32 v31, s[4:5], v37, v37, v33
	v_rcp_f32_e32 v38, v31
	s_nop 0
	v_fma_f32 v39, -v31, v38, 1.0
	v_fmac_f32_e32 v38, v39, v38
	v_div_scale_f32 v39, vcc, v33, v37, v33
	v_mul_f32_e32 v40, v39, v38
	v_fma_f32 v41, -v31, v40, v39
	v_fmac_f32_e32 v40, v41, v38
	v_fma_f32 v31, -v31, v40, v39
	v_div_fmas_f32 v31, v31, v38, v40
	v_div_fixup_f32 v31, v31, v37, v33
	v_div_scale_f32 v33, s[4:5], v36, v36, v32
	v_rcp_f32_e32 v37, v33
	s_nop 0
	v_fma_f32 v38, -v33, v37, 1.0
	v_fmac_f32_e32 v37, v38, v37
	v_div_scale_f32 v38, vcc, v32, v36, v32
	v_mul_f32_e32 v39, v38, v37
	v_fma_f32 v40, -v33, v39, v38
	v_fmac_f32_e32 v39, v40, v37
	v_fma_f32 v33, -v33, v39, v38
	v_div_fmas_f32 v33, v33, v37, v39
	v_div_fixup_f32 v32, v33, v36, v32
	v_cvt_pk_bf16_f32 v31, v32, v31
	v_lshl_add_u64 v[32:33], v[34:35], 0, v[130:131]
	v_lshlrev_b64 v[32:33], 5, v[32:33]
	v_lshl_add_u64 v[32:33], v[66:67], 0, v[32:33]
	global_store_dwordx2 v[32:33], v[30:31], off
	v_mul_f32_e32 v30, 0x3d372713, v26
	v_mul_f32_e32 v31, 0x3d372713, v27
	v_mul_f32_e32 v30, v26, v30
	v_mul_f32_e32 v31, v27, v31
	v_fma_f32 v30, v26, v30, v26
	v_fma_f32 v31, v27, v31, v27
	v_mul_f32_e32 v30, 0x3f4c422a, v30
	v_mul_f32_e32 v31, 0x3f4c422a, v31
	v_mul_f32_e32 v30, -2.0, v30
	v_mul_f32_e32 v31, -2.0, v31
	v_mul_f32_e32 v30, 0x3fb8aa3b, v30
	v_mul_f32_e32 v31, 0x3fb8aa3b, v31
	v_exp_f32_e32 v30, v30
	v_exp_f32_e32 v31, v31
	s_nop 0
	v_pk_add_f32 v[30:31], v[30:31], 1.0 op_sel_hi:[1,0]
	s_nop 0
	v_div_scale_f32 v32, s[4:5], v31, v31, v27
	v_rcp_f32_e32 v33, v32
	s_nop 0
	v_fma_f32 v36, -v32, v33, 1.0
	v_fmac_f32_e32 v33, v36, v33
	v_div_scale_f32 v36, vcc, v27, v31, v27
	v_mul_f32_e32 v37, v36, v33
	v_fma_f32 v38, -v32, v37, v36
	v_fmac_f32_e32 v37, v38, v33
	v_fma_f32 v32, -v32, v37, v36
	v_div_fmas_f32 v32, v32, v33, v37
	v_div_fixup_f32 v27, v32, v31, v27
	v_div_scale_f32 v31, s[4:5], v30, v30, v26
	v_rcp_f32_e32 v32, v31
	s_nop 0
	v_fma_f32 v33, -v31, v32, 1.0
	v_fmac_f32_e32 v32, v33, v32
	v_div_scale_f32 v33, vcc, v26, v30, v26
	v_mul_f32_e32 v36, v33, v32
	v_fma_f32 v37, -v31, v36, v33
	v_fmac_f32_e32 v36, v37, v32
	v_fma_f32 v31, -v31, v36, v33
	v_div_fmas_f32 v31, v31, v32, v36
	v_div_fixup_f32 v26, v31, v30, v26
	v_cvt_pk_bf16_f32 v26, v26, v27
	v_mul_f32_e32 v27, 0x3d372713, v28
	v_mul_f32_e32 v27, v28, v27
	v_fma_f32 v27, v28, v27, v28
	v_mul_f32_e32 v27, 0x3f4c422a, v27
	v_mul_f32_e32 v27, -2.0, v27
	v_mul_f32_e32 v27, 0x3fb8aa3b, v27
	v_exp_f32_e32 v30, v27
	v_mul_f32_e32 v27, 0x3d372713, v29
	v_mul_f32_e32 v27, v29, v27
	v_fma_f32 v27, v29, v27, v29
	v_mul_f32_e32 v27, 0x3f4c422a, v27
	v_mul_f32_e32 v27, -2.0, v27
	v_mul_f32_e32 v27, 0x3fb8aa3b, v27
	v_exp_f32_e32 v31, v27
	s_nop 0
	v_pk_add_f32 v[30:31], v[30:31], 1.0 op_sel_hi:[1,0]
	s_nop 0
	v_div_scale_f32 v27, s[4:5], v31, v31, v29
	v_rcp_f32_e32 v32, v27
	s_nop 0
	v_fma_f32 v33, -v27, v32, 1.0
	v_fmac_f32_e32 v32, v33, v32
	v_div_scale_f32 v33, vcc, v29, v31, v29
	v_mul_f32_e32 v36, v33, v32
	v_fma_f32 v37, -v27, v36, v33
	v_fmac_f32_e32 v36, v37, v32
	v_fma_f32 v27, -v27, v36, v33
	v_div_fmas_f32 v27, v27, v32, v36
	v_div_fixup_f32 v27, v27, v31, v29
	v_div_scale_f32 v29, s[4:5], v30, v30, v28
	v_rcp_f32_e32 v31, v29
	s_nop 0
	v_fma_f32 v32, -v29, v31, 1.0
	v_fmac_f32_e32 v31, v32, v31
	v_div_scale_f32 v32, vcc, v28, v30, v28
	v_mul_f32_e32 v33, v32, v31
	v_fma_f32 v36, -v29, v33, v32
	v_fmac_f32_e32 v33, v36, v31
	v_fma_f32 v29, -v29, v33, v32
	v_div_fmas_f32 v29, v29, v31, v33
	v_div_fixup_f32 v28, v29, v30, v28
	v_cvt_pk_bf16_f32 v27, v28, v27
	v_lshl_add_u64 v[28:29], v[34:35], 0, v[58:59]
	v_lshlrev_b64 v[28:29], 5, v[28:29]
	v_lshl_add_u64 v[28:29], v[66:67], 0, v[28:29]
	global_store_dwordx2 v[28:29], v[26:27], off
	v_mul_f32_e32 v26, 0x3d372713, v22
	v_mul_f32_e32 v27, 0x3d372713, v23
	v_mul_f32_e32 v26, v22, v26
	v_mul_f32_e32 v27, v23, v27
	v_fma_f32 v26, v22, v26, v22
	v_fma_f32 v27, v23, v27, v23
	v_mul_f32_e32 v26, 0x3f4c422a, v26
	v_mul_f32_e32 v27, 0x3f4c422a, v27
	v_mul_f32_e32 v26, -2.0, v26
	v_mul_f32_e32 v27, -2.0, v27
	v_mul_f32_e32 v26, 0x3fb8aa3b, v26
	v_mul_f32_e32 v27, 0x3fb8aa3b, v27
	v_exp_f32_e32 v26, v26
	v_exp_f32_e32 v27, v27
	s_nop 0
	v_pk_add_f32 v[26:27], v[26:27], 1.0 op_sel_hi:[1,0]
	s_nop 0
	v_div_scale_f32 v28, s[4:5], v27, v27, v23
	v_rcp_f32_e32 v29, v28
	s_nop 0
	v_fma_f32 v30, -v28, v29, 1.0
	v_fmac_f32_e32 v29, v30, v29
	v_div_scale_f32 v30, vcc, v23, v27, v23
	v_mul_f32_e32 v31, v30, v29
	v_fma_f32 v32, -v28, v31, v30
	v_fmac_f32_e32 v31, v32, v29
	v_fma_f32 v28, -v28, v31, v30
	v_div_fmas_f32 v28, v28, v29, v31
	v_div_fixup_f32 v23, v28, v27, v23
	v_div_scale_f32 v27, s[4:5], v26, v26, v22
	v_rcp_f32_e32 v28, v27
	s_nop 0
	v_fma_f32 v29, -v27, v28, 1.0
	v_fmac_f32_e32 v28, v29, v28
	v_div_scale_f32 v29, vcc, v22, v26, v22
	v_mul_f32_e32 v30, v29, v28
	v_fma_f32 v31, -v27, v30, v29
	v_fmac_f32_e32 v30, v31, v28
	v_fma_f32 v27, -v27, v30, v29
	v_div_fmas_f32 v27, v27, v28, v30
	v_div_fixup_f32 v22, v27, v26, v22
	v_cvt_pk_bf16_f32 v22, v22, v23
	v_mul_f32_e32 v23, 0x3d372713, v24
	v_mul_f32_e32 v23, v24, v23
	v_fma_f32 v23, v24, v23, v24
	v_mul_f32_e32 v23, 0x3f4c422a, v23
	v_mul_f32_e32 v23, -2.0, v23
	v_mul_f32_e32 v23, 0x3fb8aa3b, v23
	v_exp_f32_e32 v26, v23
	v_mul_f32_e32 v23, 0x3d372713, v25
	v_mul_f32_e32 v23, v25, v23
	v_fma_f32 v23, v25, v23, v25
	v_mul_f32_e32 v23, 0x3f4c422a, v23
	v_mul_f32_e32 v23, -2.0, v23
	v_mul_f32_e32 v23, 0x3fb8aa3b, v23
	v_exp_f32_e32 v27, v23
	s_nop 0
	v_pk_add_f32 v[26:27], v[26:27], 1.0 op_sel_hi:[1,0]
	s_nop 0
	v_div_scale_f32 v23, s[4:5], v27, v27, v25
	v_rcp_f32_e32 v28, v23
	s_nop 0
	v_fma_f32 v29, -v23, v28, 1.0
	v_fmac_f32_e32 v28, v29, v28
	v_div_scale_f32 v29, vcc, v25, v27, v25
	v_mul_f32_e32 v30, v29, v28
	v_fma_f32 v31, -v23, v30, v29
	v_fmac_f32_e32 v30, v31, v28
	v_fma_f32 v23, -v23, v30, v29
	v_div_fmas_f32 v23, v23, v28, v30
	v_div_fixup_f32 v23, v23, v27, v25
	v_div_scale_f32 v25, s[4:5], v26, v26, v24
	v_rcp_f32_e32 v27, v25
	s_nop 0
	v_fma_f32 v28, -v25, v27, 1.0
	v_fmac_f32_e32 v27, v28, v27
	v_div_scale_f32 v28, vcc, v24, v26, v24
	v_mul_f32_e32 v29, v28, v27
	v_fma_f32 v30, -v25, v29, v28
	v_fmac_f32_e32 v29, v30, v27
	v_fma_f32 v25, -v25, v29, v28
	v_div_fmas_f32 v25, v25, v27, v29
	v_div_fixup_f32 v24, v25, v26, v24
	v_cvt_pk_bf16_f32 v23, v24, v23
	v_lshl_add_u64 v[24:25], v[34:35], 0, v[54:55]
	v_lshlrev_b64 v[24:25], 5, v[24:25]
	v_lshl_add_u64 v[24:25], v[66:67], 0, v[24:25]
	global_store_dwordx2 v[24:25], v[22:23], off
	v_mul_f32_e32 v22, 0x3d372713, v18
	v_mul_f32_e32 v23, 0x3d372713, v19
	v_mul_f32_e32 v22, v18, v22
	v_mul_f32_e32 v23, v19, v23
	v_fma_f32 v22, v18, v22, v18
	v_fma_f32 v23, v19, v23, v19
	v_mul_f32_e32 v22, 0x3f4c422a, v22
	v_mul_f32_e32 v23, 0x3f4c422a, v23
	v_mul_f32_e32 v22, -2.0, v22
	v_mul_f32_e32 v23, -2.0, v23
	v_mul_f32_e32 v22, 0x3fb8aa3b, v22
	v_mul_f32_e32 v23, 0x3fb8aa3b, v23
	v_exp_f32_e32 v22, v22
	v_exp_f32_e32 v23, v23
	s_nop 0
	v_pk_add_f32 v[22:23], v[22:23], 1.0 op_sel_hi:[1,0]
	s_nop 0
	v_div_scale_f32 v24, s[4:5], v23, v23, v19
	v_rcp_f32_e32 v25, v24
	s_nop 0
	v_fma_f32 v26, -v24, v25, 1.0
	v_fmac_f32_e32 v25, v26, v25
	v_div_scale_f32 v26, vcc, v19, v23, v19
	v_mul_f32_e32 v27, v26, v25
	v_fma_f32 v28, -v24, v27, v26
	v_fmac_f32_e32 v27, v28, v25
	v_fma_f32 v24, -v24, v27, v26
	v_div_fmas_f32 v24, v24, v25, v27
	v_div_fixup_f32 v19, v24, v23, v19
	v_div_scale_f32 v23, s[4:5], v22, v22, v18
	v_rcp_f32_e32 v24, v23
	s_nop 0
	v_fma_f32 v25, -v23, v24, 1.0
	v_fmac_f32_e32 v24, v25, v24
	v_div_scale_f32 v25, vcc, v18, v22, v18
	v_mul_f32_e32 v26, v25, v24
	v_fma_f32 v27, -v23, v26, v25
	v_fmac_f32_e32 v26, v27, v24
	v_fma_f32 v23, -v23, v26, v25
	v_div_fmas_f32 v23, v23, v24, v26
	v_div_fixup_f32 v18, v23, v22, v18
	v_cvt_pk_bf16_f32 v18, v18, v19
	v_mul_f32_e32 v19, 0x3d372713, v20
	v_mul_f32_e32 v19, v20, v19
	v_fma_f32 v19, v20, v19, v20
	v_mul_f32_e32 v19, 0x3f4c422a, v19
	v_mul_f32_e32 v19, -2.0, v19
	v_mul_f32_e32 v19, 0x3fb8aa3b, v19
	v_exp_f32_e32 v22, v19
	v_mul_f32_e32 v19, 0x3d372713, v21
	v_mul_f32_e32 v19, v21, v19
	v_fma_f32 v19, v21, v19, v21
	v_mul_f32_e32 v19, 0x3f4c422a, v19
	v_mul_f32_e32 v19, -2.0, v19
	v_mul_f32_e32 v19, 0x3fb8aa3b, v19
	v_exp_f32_e32 v23, v19
	s_nop 0
	v_pk_add_f32 v[22:23], v[22:23], 1.0 op_sel_hi:[1,0]
	s_nop 0
	v_div_scale_f32 v19, s[4:5], v23, v23, v21
	v_rcp_f32_e32 v24, v19
	s_nop 0
	v_fma_f32 v25, -v19, v24, 1.0
	v_fmac_f32_e32 v24, v25, v24
	v_div_scale_f32 v25, vcc, v21, v23, v21
	v_mul_f32_e32 v26, v25, v24
	v_fma_f32 v27, -v19, v26, v25
	v_fmac_f32_e32 v26, v27, v24
	v_fma_f32 v19, -v19, v26, v25
	v_div_fmas_f32 v19, v19, v24, v26
	v_div_fixup_f32 v19, v19, v23, v21
	v_div_scale_f32 v21, s[4:5], v22, v22, v20
	v_rcp_f32_e32 v23, v21
	s_nop 0
	v_fma_f32 v24, -v21, v23, 1.0
	v_fmac_f32_e32 v23, v24, v23
	v_div_scale_f32 v24, vcc, v20, v22, v20
	v_mul_f32_e32 v25, v24, v23
	v_fma_f32 v26, -v21, v25, v24
	v_fmac_f32_e32 v25, v26, v23
	v_fma_f32 v21, -v21, v25, v24
	v_div_fmas_f32 v21, v21, v23, v25
	v_div_fixup_f32 v20, v21, v22, v20
	v_cvt_pk_bf16_f32 v19, v20, v19
	v_lshl_add_u64 v[20:21], v[34:35], 0, v[50:51]
	v_lshlrev_b64 v[20:21], 5, v[20:21]
	v_lshl_add_u64 v[20:21], v[66:67], 0, v[20:21]
	global_store_dwordx2 v[20:21], v[18:19], off
	v_or_b32_e32 v18, 3, v1
	v_mul_f32_e32 v1, 0x3d372713, v14
	v_mul_f32_e32 v1, v14, v1
	v_fma_f32 v1, v14, v1, v14
	v_mul_f32_e32 v1, 0x3f4c422a, v1
	v_mul_f32_e32 v1, -2.0, v1
	v_mul_f32_e32 v1, 0x3fb8aa3b, v1
	v_exp_f32_e32 v20, v1
	v_mul_f32_e32 v1, 0x3d372713, v15
	v_mul_f32_e32 v1, v15, v1
	v_fma_f32 v1, v15, v1, v15
	v_mul_f32_e32 v1, 0x3f4c422a, v1
	v_mul_f32_e32 v1, -2.0, v1
	v_mul_f32_e32 v1, 0x3fb8aa3b, v1
	v_exp_f32_e32 v21, v1
	v_ashrrev_i32_e32 v19, 31, v18
	v_lshl_add_u64 v[18:19], s[2:3], 0, v[18:19]
	v_pk_add_f32 v[20:21], v[20:21], 1.0 op_sel_hi:[1,0]
	s_nop 0
	v_div_scale_f32 v1, s[2:3], v21, v21, v15
	v_rcp_f32_e32 v22, v1
	s_nop 0
	v_fma_f32 v23, -v1, v22, 1.0
	v_fmac_f32_e32 v22, v23, v22
	v_div_scale_f32 v23, vcc, v15, v21, v15
	v_mul_f32_e32 v24, v23, v22
	v_fma_f32 v25, -v1, v24, v23
	v_fmac_f32_e32 v24, v25, v22
	v_fma_f32 v1, -v1, v24, v23
	v_div_fmas_f32 v1, v1, v22, v24
	v_div_fixup_f32 v1, v1, v21, v15
	v_div_scale_f32 v15, s[2:3], v20, v20, v14
	v_rcp_f32_e32 v21, v15
	s_nop 0
	v_fma_f32 v22, -v15, v21, 1.0
	v_fmac_f32_e32 v21, v22, v21
	v_div_scale_f32 v22, vcc, v14, v20, v14
	v_mul_f32_e32 v23, v22, v21
	v_fma_f32 v24, -v15, v23, v22
	v_fmac_f32_e32 v23, v24, v21
	v_fma_f32 v15, -v15, v23, v22
	v_div_fmas_f32 v15, v15, v21, v23
	v_div_fixup_f32 v14, v15, v20, v14
	v_cvt_pk_bf16_f32 v14, v14, v1
	v_mul_f32_e32 v1, 0x3d372713, v16
	v_mul_f32_e32 v1, v16, v1
	v_fma_f32 v1, v16, v1, v16
	v_mul_f32_e32 v1, 0x3f4c422a, v1
	v_mul_f32_e32 v1, -2.0, v1
	v_mul_f32_e32 v1, 0x3fb8aa3b, v1
	v_exp_f32_e32 v20, v1
	v_mul_f32_e32 v1, 0x3d372713, v17
	v_mul_f32_e32 v1, v17, v1
	v_fma_f32 v1, v17, v1, v17
	v_mul_f32_e32 v1, 0x3f4c422a, v1
	v_mul_f32_e32 v1, -2.0, v1
	v_mul_f32_e32 v1, 0x3fb8aa3b, v1
	v_exp_f32_e32 v21, v1
	s_nop 0
	v_pk_add_f32 v[20:21], v[20:21], 1.0 op_sel_hi:[1,0]
	s_nop 0
	v_div_scale_f32 v1, s[2:3], v21, v21, v17
	v_rcp_f32_e32 v15, v1
	s_nop 0
	v_fma_f32 v22, -v1, v15, 1.0
	v_fmac_f32_e32 v15, v22, v15
	v_div_scale_f32 v22, vcc, v17, v21, v17
	v_mul_f32_e32 v23, v22, v15
	v_fma_f32 v24, -v1, v23, v22
	v_fmac_f32_e32 v23, v24, v15
	v_fma_f32 v1, -v1, v23, v22
	v_div_fmas_f32 v1, v1, v15, v23
	v_div_scale_f32 v15, s[2:3], v20, v20, v16
	v_div_fixup_f32 v1, v1, v21, v17
	v_rcp_f32_e32 v17, v15
	s_nop 0
	v_fma_f32 v21, -v15, v17, 1.0
	v_fmac_f32_e32 v17, v21, v17
	v_div_scale_f32 v21, vcc, v16, v20, v16
	v_mul_f32_e32 v22, v21, v17
	v_fma_f32 v23, -v15, v22, v21
	v_fmac_f32_e32 v22, v23, v17
	v_fma_f32 v15, -v15, v22, v21
	v_div_fmas_f32 v15, v15, v17, v22
	v_div_fixup_f32 v15, v15, v20, v16
	v_cvt_pk_bf16_f32 v15, v15, v1
	v_mul_f32_e32 v1, 0x3d372713, v10
	v_mul_f32_e32 v1, v10, v1
	v_fma_f32 v1, v10, v1, v10
	v_lshl_add_u64 v[16:17], v[18:19], 0, v[130:131]
	v_mul_f32_e32 v1, 0x3f4c422a, v1
	v_lshlrev_b64 v[16:17], 5, v[16:17]
	v_mul_f32_e32 v1, -2.0, v1
	v_lshl_add_u64 v[16:17], v[66:67], 0, v[16:17]
	v_mul_f32_e32 v1, 0x3fb8aa3b, v1
	global_store_dwordx2 v[16:17], v[14:15], off
	v_exp_f32_e32 v14, v1
	v_mul_f32_e32 v1, 0x3d372713, v11
	v_mul_f32_e32 v1, v11, v1
	v_fma_f32 v1, v11, v1, v11
	v_mul_f32_e32 v1, 0x3f4c422a, v1
	v_mul_f32_e32 v1, -2.0, v1
	v_mul_f32_e32 v1, 0x3fb8aa3b, v1
	v_exp_f32_e32 v15, v1
	s_nop 0
	v_pk_add_f32 v[14:15], v[14:15], 1.0 op_sel_hi:[1,0]
	s_nop 0
	v_div_scale_f32 v1, s[2:3], v15, v15, v11
	v_rcp_f32_e32 v16, v1
	s_nop 0
	v_fma_f32 v17, -v1, v16, 1.0
	v_fmac_f32_e32 v16, v17, v16
	v_div_scale_f32 v17, vcc, v11, v15, v11
	v_mul_f32_e32 v20, v17, v16
	v_fma_f32 v21, -v1, v20, v17
	v_fmac_f32_e32 v20, v21, v16
	v_fma_f32 v1, -v1, v20, v17
	v_div_fmas_f32 v1, v1, v16, v20
	v_div_fixup_f32 v1, v1, v15, v11
	v_div_scale_f32 v11, s[2:3], v14, v14, v10
	v_rcp_f32_e32 v15, v11
	s_nop 0
	v_fma_f32 v16, -v11, v15, 1.0
	v_fmac_f32_e32 v15, v16, v15
	v_div_scale_f32 v16, vcc, v10, v14, v10
	v_mul_f32_e32 v17, v16, v15
	v_fma_f32 v20, -v11, v17, v16
	v_fmac_f32_e32 v17, v20, v15
	v_fma_f32 v11, -v11, v17, v16
	v_div_fmas_f32 v11, v11, v15, v17
	v_div_fixup_f32 v10, v11, v14, v10
	v_cvt_pk_bf16_f32 v10, v10, v1
	v_mul_f32_e32 v1, 0x3d372713, v12
	v_mul_f32_e32 v1, v12, v1
	v_fma_f32 v1, v12, v1, v12
	v_mul_f32_e32 v1, 0x3f4c422a, v1
	v_mul_f32_e32 v1, -2.0, v1
	v_mul_f32_e32 v1, 0x3fb8aa3b, v1
	v_exp_f32_e32 v14, v1
	v_mul_f32_e32 v1, 0x3d372713, v13
	v_mul_f32_e32 v1, v13, v1
	v_fma_f32 v1, v13, v1, v13
	v_mul_f32_e32 v1, 0x3f4c422a, v1
	v_mul_f32_e32 v1, -2.0, v1
	v_mul_f32_e32 v1, 0x3fb8aa3b, v1
	v_exp_f32_e32 v15, v1
	s_nop 0
	v_pk_add_f32 v[14:15], v[14:15], 1.0 op_sel_hi:[1,0]
	s_nop 0
	v_div_scale_f32 v1, s[2:3], v15, v15, v13
	v_rcp_f32_e32 v11, v1
	s_nop 0
	v_fma_f32 v16, -v1, v11, 1.0
	v_fmac_f32_e32 v11, v16, v11
	v_div_scale_f32 v16, vcc, v13, v15, v13
	v_mul_f32_e32 v17, v16, v11
	v_fma_f32 v20, -v1, v17, v16
	v_fmac_f32_e32 v17, v20, v11
	v_fma_f32 v1, -v1, v17, v16
	v_div_fmas_f32 v1, v1, v11, v17
	v_div_scale_f32 v11, s[2:3], v14, v14, v12
	v_div_fixup_f32 v1, v1, v15, v13
	v_rcp_f32_e32 v13, v11
	s_nop 0
	v_fma_f32 v15, -v11, v13, 1.0
	v_fmac_f32_e32 v13, v15, v13
	v_div_scale_f32 v15, vcc, v12, v14, v12
	v_mul_f32_e32 v16, v15, v13
	v_fma_f32 v17, -v11, v16, v15
	v_fmac_f32_e32 v16, v17, v13
	v_fma_f32 v11, -v11, v16, v15
	v_div_fmas_f32 v11, v11, v13, v16
	v_div_fixup_f32 v11, v11, v14, v12
	v_cvt_pk_bf16_f32 v11, v11, v1
	v_mul_f32_e32 v1, 0x3d372713, v6
	v_mul_f32_e32 v1, v6, v1
	v_fma_f32 v1, v6, v1, v6
	v_lshl_add_u64 v[12:13], v[18:19], 0, v[58:59]
	v_mul_f32_e32 v1, 0x3f4c422a, v1
	v_lshlrev_b64 v[12:13], 5, v[12:13]
	v_mul_f32_e32 v1, -2.0, v1
	v_lshl_add_u64 v[12:13], v[66:67], 0, v[12:13]
	v_mul_f32_e32 v1, 0x3fb8aa3b, v1
	global_store_dwordx2 v[12:13], v[10:11], off
	v_exp_f32_e32 v10, v1
	v_mul_f32_e32 v1, 0x3d372713, v7
	v_mul_f32_e32 v1, v7, v1
	v_fma_f32 v1, v7, v1, v7
	v_mul_f32_e32 v1, 0x3f4c422a, v1
	v_mul_f32_e32 v1, -2.0, v1
	v_mul_f32_e32 v1, 0x3fb8aa3b, v1
	v_exp_f32_e32 v11, v1
	s_nop 0
	v_pk_add_f32 v[10:11], v[10:11], 1.0 op_sel_hi:[1,0]
	s_nop 0
	v_div_scale_f32 v1, s[2:3], v11, v11, v7
	v_rcp_f32_e32 v12, v1
	s_nop 0
	v_fma_f32 v13, -v1, v12, 1.0
	v_fmac_f32_e32 v12, v13, v12
	v_div_scale_f32 v13, vcc, v7, v11, v7
	v_mul_f32_e32 v14, v13, v12
	v_fma_f32 v15, -v1, v14, v13
	v_fmac_f32_e32 v14, v15, v12
	v_fma_f32 v1, -v1, v14, v13
	v_div_fmas_f32 v1, v1, v12, v14
	v_div_fixup_f32 v1, v1, v11, v7
	v_div_scale_f32 v7, s[2:3], v10, v10, v6
	v_rcp_f32_e32 v11, v7
	s_nop 0
	v_fma_f32 v12, -v7, v11, 1.0
	v_fmac_f32_e32 v11, v12, v11
	v_div_scale_f32 v12, vcc, v6, v10, v6
	v_mul_f32_e32 v13, v12, v11
	v_fma_f32 v14, -v7, v13, v12
	v_fmac_f32_e32 v13, v14, v11
	v_fma_f32 v7, -v7, v13, v12
	v_div_fmas_f32 v7, v7, v11, v13
	v_div_fixup_f32 v6, v7, v10, v6
	v_cvt_pk_bf16_f32 v6, v6, v1
	v_mul_f32_e32 v1, 0x3d372713, v8
	v_mul_f32_e32 v1, v8, v1
	v_fma_f32 v1, v8, v1, v8
	v_mul_f32_e32 v1, 0x3f4c422a, v1
	v_mul_f32_e32 v1, -2.0, v1
	v_mul_f32_e32 v1, 0x3fb8aa3b, v1
	v_exp_f32_e32 v10, v1
	v_mul_f32_e32 v1, 0x3d372713, v9
	v_mul_f32_e32 v1, v9, v1
	v_fma_f32 v1, v9, v1, v9
	v_mul_f32_e32 v1, 0x3f4c422a, v1
	v_mul_f32_e32 v1, -2.0, v1
	v_mul_f32_e32 v1, 0x3fb8aa3b, v1
	v_exp_f32_e32 v11, v1
	s_nop 0
	v_pk_add_f32 v[10:11], v[10:11], 1.0 op_sel_hi:[1,0]
	s_nop 0
	v_div_scale_f32 v1, s[2:3], v11, v11, v9
	v_rcp_f32_e32 v7, v1
	s_nop 0
	v_fma_f32 v12, -v1, v7, 1.0
	v_fmac_f32_e32 v7, v12, v7
	v_div_scale_f32 v12, vcc, v9, v11, v9
	v_mul_f32_e32 v13, v12, v7
	v_fma_f32 v14, -v1, v13, v12
	v_fmac_f32_e32 v13, v14, v7
	v_fma_f32 v1, -v1, v13, v12
	v_div_fmas_f32 v1, v1, v7, v13
	v_div_scale_f32 v7, s[2:3], v10, v10, v8
	v_div_fixup_f32 v1, v1, v11, v9
	v_rcp_f32_e32 v9, v7
	s_nop 0
	v_fma_f32 v11, -v7, v9, 1.0
	v_fmac_f32_e32 v9, v11, v9
	v_div_scale_f32 v11, vcc, v8, v10, v8
	v_mul_f32_e32 v12, v11, v9
	v_fma_f32 v13, -v7, v12, v11
	v_fmac_f32_e32 v12, v13, v9
	v_fma_f32 v7, -v7, v12, v11
	v_div_fmas_f32 v7, v7, v9, v12
	v_div_fixup_f32 v7, v7, v10, v8
	v_cvt_pk_bf16_f32 v7, v7, v1
	v_mul_f32_e32 v1, 0x3d372713, v2
	v_mul_f32_e32 v1, v2, v1
	v_fma_f32 v1, v2, v1, v2
	v_lshl_add_u64 v[8:9], v[18:19], 0, v[54:55]
	v_mul_f32_e32 v1, 0x3f4c422a, v1
	v_lshlrev_b64 v[8:9], 5, v[8:9]
	v_mul_f32_e32 v1, -2.0, v1
	v_lshl_add_u64 v[8:9], v[66:67], 0, v[8:9]
	v_mul_f32_e32 v1, 0x3fb8aa3b, v1
	global_store_dwordx2 v[8:9], v[6:7], off
	v_exp_f32_e32 v6, v1
	v_mul_f32_e32 v1, 0x3d372713, v3
	v_mul_f32_e32 v1, v3, v1
	v_fma_f32 v1, v3, v1, v3
	v_mul_f32_e32 v1, 0x3f4c422a, v1
	v_mul_f32_e32 v1, -2.0, v1
	v_mul_f32_e32 v1, 0x3fb8aa3b, v1
	v_exp_f32_e32 v7, v1
	s_nop 0
	v_pk_add_f32 v[6:7], v[6:7], 1.0 op_sel_hi:[1,0]
	s_nop 0
	v_div_scale_f32 v1, s[2:3], v7, v7, v3
	v_rcp_f32_e32 v8, v1
	s_nop 0
	v_fma_f32 v9, -v1, v8, 1.0
	v_fmac_f32_e32 v8, v9, v8
	v_div_scale_f32 v9, vcc, v3, v7, v3
	v_mul_f32_e32 v10, v9, v8
	v_fma_f32 v11, -v1, v10, v9
	v_fmac_f32_e32 v10, v11, v8
	v_fma_f32 v1, -v1, v10, v9
	v_div_fmas_f32 v1, v1, v8, v10
	v_div_fixup_f32 v1, v1, v7, v3
	v_div_scale_f32 v3, s[2:3], v6, v6, v2
	v_rcp_f32_e32 v7, v3
	s_nop 0
	v_fma_f32 v8, -v3, v7, 1.0
	v_fmac_f32_e32 v7, v8, v7
	v_div_scale_f32 v8, vcc, v2, v6, v2
	v_mul_f32_e32 v9, v8, v7
	v_fma_f32 v10, -v3, v9, v8
	v_fmac_f32_e32 v9, v10, v7
	v_fma_f32 v3, -v3, v9, v8
	v_div_fmas_f32 v3, v3, v7, v9
	v_div_fixup_f32 v2, v3, v6, v2
	v_cvt_pk_bf16_f32 v2, v2, v1
	v_mul_f32_e32 v1, 0x3d372713, v4
	v_mul_f32_e32 v1, v4, v1
	v_fma_f32 v1, v4, v1, v4
	v_mul_f32_e32 v1, 0x3f4c422a, v1
	v_mul_f32_e32 v1, -2.0, v1
	v_mul_f32_e32 v1, 0x3fb8aa3b, v1
	v_exp_f32_e32 v6, v1
	v_mul_f32_e32 v1, 0x3d372713, v5
	v_mul_f32_e32 v1, v5, v1
	v_fma_f32 v1, v5, v1, v5
	v_mul_f32_e32 v1, 0x3f4c422a, v1
	v_mul_f32_e32 v1, -2.0, v1
	v_mul_f32_e32 v1, 0x3fb8aa3b, v1
	v_exp_f32_e32 v7, v1
	s_nop 0
	v_pk_add_f32 v[6:7], v[6:7], 1.0 op_sel_hi:[1,0]
	s_nop 0
	v_div_scale_f32 v1, s[2:3], v7, v7, v5
	v_rcp_f32_e32 v3, v1
	s_nop 0
	v_fma_f32 v8, -v1, v3, 1.0
	v_fmac_f32_e32 v3, v8, v3
	v_div_scale_f32 v8, vcc, v5, v7, v5
	v_mul_f32_e32 v9, v8, v3
	v_fma_f32 v10, -v1, v9, v8
	v_fmac_f32_e32 v9, v10, v3
	v_fma_f32 v1, -v1, v9, v8
	v_div_fmas_f32 v1, v1, v3, v9
	v_div_scale_f32 v3, s[2:3], v6, v6, v4
	v_div_fixup_f32 v1, v1, v7, v5
	v_rcp_f32_e32 v5, v3
	s_nop 0
	v_fma_f32 v7, -v3, v5, 1.0
	v_fmac_f32_e32 v5, v7, v5
	v_div_scale_f32 v7, vcc, v4, v6, v4
	v_mul_f32_e32 v8, v7, v5
	v_fma_f32 v9, -v3, v8, v7
	v_fmac_f32_e32 v8, v9, v5
	v_fma_f32 v3, -v3, v8, v7
	v_div_fmas_f32 v3, v3, v5, v8
	v_div_fixup_f32 v3, v3, v6, v4
	v_lshl_add_u64 v[4:5], v[18:19], 0, v[50:51]
	v_lshlrev_b64 v[4:5], 5, v[4:5]
	v_cvt_pk_bf16_f32 v3, v3, v1
	v_lshl_add_u64 v[4:5], v[66:67], 0, v[4:5]
	global_store_dwordx2 v[4:5], v[2:3], off
	s_barrier

.LBB0_457:
	s_cmp_ge_i32 s21, s16
	s_mov_b64 s[0:1], -1
	s_cbranch_scc0 .LBB0_543
	v_readlane_b32 s0, v254, 52
	s_cmp_ge_i32 s21, s0
	s_mov_b64 s[0:1], -1
	s_cbranch_scc0 .LBB0_540
	s_sub_i32 s88, s21, s16
	v_readlane_b32 s0, v254, 56
	s_cmp_ge_u32 s21, s0
	s_mov_b64 s[0:1], -1
	s_cbranch_scc0 .LBB0_535
	s_add_i32 s0, s88, 0xf5e0
	s_sext_i32_i16 s1, s0
	s_mulk_i32 s1, 0x2aab
	s_lshr_b32 s2, s1, 31
	s_ashr_i32 s1, s1, 18
	s_add_i32 s90, s1, s2
	s_mul_i32 s1, s90, 24
	v_mov_b32_e32 v1, v0
	s_sub_i32 s0, s0, s1
	s_sext_i32_i16 s91, s0
	v_lshlrev_b32_e32 v76, 3, v1
	s_lshl_b32 s0, s91, 6
	v_and_b32_e32 v78, 56, v76
	v_or_b32_e32 v64, s0, v78
	v_readlane_b32 s2, v254, 58
	v_ashrrev_i32_e32 v65, 31, v64
	v_readlane_b32 s3, v254, 59
	v_ashrrev_i32_e32 v77, 3, v1
	s_cmpk_gt_i32 s88, 0x161f
	s_waitcnt vmcnt(0)
	v_lshl_add_u64 v[2:3], v[64:65], 2, s[2:3]
	global_load_dwordx4 v[6:9], v[2:3], off offset:16
	s_nop 0
	global_load_dwordx4 v[2:5], v[2:3], off
	s_mov_b64 s[2:3], -1
	v_lshlrev_b32_e32 v130, 1, v78
	s_cbranch_scc1 .LBB0_496
	s_lshl_b32 s1, s90, 1
	s_and_b32 s5, s1, 62
	s_lshl_b32 s1, s90, 7
	s_and_b32 s4, s1, 0xfffff000
	s_ashr_i32 s1, s0, 31
	s_add_i32 s5, s5, -1
	s_lshl_b64 s[2:3], s[0:1], 1
	v_readlane_b32 s6, v254, 1
	v_readlane_b32 s7, v254, 2
	s_add_u32 s2, s6, s2
	v_ashrrev_i32_e32 v10, 9, v1
	s_addc_u32 s3, s7, s3
	v_add_u32_e32 v11, s5, v10
	v_lshl_add_u64 v[42:43], s[2:3], 0, v[130:131]
	v_cmp_gt_u32_e32 vcc, 64, v11
	v_mov_b32_e32 v10, 0
	v_bfe_u32 v82, v1, 3, 6
	v_mov_b32_e32 v14, 0
	v_mov_b32_e32 v15, 0
	v_mov_b32_e32 v16, 0
	v_mov_b32_e32 v17, 0
	s_waitcnt vmcnt(63) expcnt(7) lgkmcnt(15)
	s_barrier
	v_readlane_b32 s62, v254, 60
	v_readlane_b32 s63, v254, 61
	s_lshl_b32 s64, s91, 8
	s_add_u32 s62, s62, s64
	s_addc_u32 s63, s63, 0
	s_add_u32 s62, s62, -16
	s_addc_u32 s63, s63, -1
	v_lshrrev_b32_e32 v106, 4, v1
	v_mul_u32_u24_e32 v106, 0x1800, v106
	v_and_b32_e32 v107, 15, v1
	v_lshl_add_u32 v106, v107, 4, v106
	s_movk_i32 s64, 0x90
	v_cmp_gt_u32_e64 s[64:65], s64, v1
	s_nop 1
	s_and_saveexec_b64 s[64:65], s[64:65]
	global_load_dwordx4 v[100:103], v106, s[62:63]
	s_or_b64 exec, exec, s[64:65]
	s_and_saveexec_b64 s[2:3], vcc
	s_cbranch_execz .LBB0_463
	v_lshlrev_b32_e32 v11, 6, v11
	v_or3_b32 v11, v11, v82, s4
	s_movk_i32 s1, 0xc00
	v_mul_lo_u32 v12, v11, s1
	v_ashrrev_i32_e32 v13, 31, v12
	v_lshl_add_u64 v[12:13], v[42:43], 0, v[12:13]
	global_load_dwordx4 v[14:17], v[12:13], off

.LBB0_477:
	s_or_b64 exec, exec, s[2:3]
	v_add_u32_e32 v81, 32, v77
	v_add_u32_e32 v79, 0x60, v77
	v_lshlrev_b32_e32 v42, 4, v1
	v_and_b32_e32 v83, 63, v81
	v_and_b32_e32 v84, 63, v79
	v_readlane_b32 s14, v254, 60
	s_waitcnt vmcnt(0)
	v_add_u32_e32 v104, 0x10200, v42
	ds_write_b128 v104, v[100:103]
	v_and_b32_e32 v105, 7, v1
	v_lshlrev_b32_e32 v105, 5, v105
	v_add_u32_e32 v105, 0x10200, v105
	ds_write_b128 v42, v[14:17] offset:33280
	ds_write_b128 v42, v[10:13] offset:37376
	ds_write_b128 v42, v[22:25] offset:41472
	ds_write_b128 v42, v[18:21] offset:45568
	ds_write_b128 v42, v[30:33] offset:49664
	ds_write_b128 v42, v[26:29] offset:53760
	ds_write_b128 v42, v[38:41] offset:57856
	ds_write_b128 v42, v[34:37] offset:61952
	v_lshlrev_b64 v[10:11], 2, v[64:65]
	v_add_u32_e32 v85, -1, v82
	v_add_u32_e32 v86, -1, v83
	v_add_u32_e32 v87, -1, v84
	v_readlane_b32 s15, v254, 61
	v_lshl_add_u64 v[72:73], s[54:55], 0, v[10:11]
	v_add_u32_e32 v80, 64, v77
	v_cmp_gt_u32_e32 vcc, 64, v85
	v_cmp_gt_u32_e64 s[2:3], 64, v86
	v_cmp_gt_u32_e64 s[4:5], 64, v87
	v_add_u32_e32 v88, 1, v82
	v_cmp_ne_u32_e64 s[6:7], 63, v82
	v_cmp_ne_u32_e64 s[8:9], 63, v83
	v_add_u32_e32 v89, 1, v83
	v_cmp_ne_u32_e64 s[10:11], 63, v84
	v_add_u32_e32 v90, 1, v84
	v_lshl_add_u64 v[74:75], s[14:15], 0, v[10:11]
	s_mov_b32 s1, 0
	v_mov_b64_e32 v[70:71], v[2:3]
	v_mov_b64_e32 v[68:69], v[4:5]
	v_mov_b64_e32 v[66:67], v[6:7]
	v_mov_b64_e32 v[62:63], v[8:9]
	v_mov_b64_e32 v[60:61], v[2:3]
	v_mov_b64_e32 v[58:59], v[4:5]
	v_mov_b64_e32 v[56:57], v[6:7]
	v_mov_b64_e32 v[54:55], v[8:9]
	v_mov_b64_e32 v[52:53], v[2:3]
	v_mov_b64_e32 v[50:51], v[4:5]
	v_mov_b64_e32 v[48:49], v[6:7]
	v_mov_b64_e32 v[46:47], v[8:9]
	v_mov_b64_e32 v[44:45], v[2:3]
	v_mov_b64_e32 v[42:43], v[4:5]
	v_mov_b64_e32 v[40:41], v[6:7]
	v_mov_b64_e32 v[38:39], v[8:9]
	s_waitcnt lgkmcnt(0)
	s_barrier
	s_branch .LBB0_479
.LBB0_478:
	s_or_b64 exec, exec, s[14:15]
	s_add_i32 s1, s1, 3
	s_mov_b64 s[14:15], 0x4800
	s_cmp_eq_u32 s1, 9
	v_lshl_add_u64 v[74:75], v[74:75], 0, s[14:15]
	v_add_u32_e32 v105, 0x300, v105
	s_cbranch_scc1 .LBB0_495
.LBB0_479:
	ds_read_b128 v[10:13], v105 offset:16
	ds_read_b128 v[14:17], v105
	s_mul_i32 s27, s1, 0xab
	s_lshr_b32 s14, s27, 3
	s_and_b32 s28, s14, 0x1fc0
	s_and_saveexec_b64 s[14:15], vcc
	s_cbranch_execz .LBB0_483
	v_add_u32_e32 v18, s28, v77
	s_mov_b32 s18, 0x1ffffc0
	v_and_or_b32 v18, v18, s18, v85
	v_lshl_or_b32 v18, v18, 7, v130
	ds_read_b128 v[18:21], v18 offset:33280
	s_waitcnt vmcnt(2) lgkmcnt(0)
	v_lshlrev_b32_e32 v22, 16, v18
	v_and_b32_e32 v23, 0xffff0000, v18
	v_lshlrev_b32_e32 v18, 16, v19
	v_and_b32_e32 v19, 0xffff0000, v19
	s_waitcnt vmcnt(0)
	v_pk_fma_f32 v[68:69], v[16:17], v[18:19], v[68:69]
	v_lshlrev_b32_e32 v18, 16, v20
	v_and_b32_e32 v19, 0xffff0000, v20
	v_pk_fma_f32 v[66:67], v[10:11], v[18:19], v[66:67]
	v_lshlrev_b32_e32 v18, 16, v21
	v_and_b32_e32 v19, 0xffff0000, v21
	v_pk_fma_f32 v[70:71], v[14:15], v[22:23], v[70:71]
	v_pk_fma_f32 v[62:63], v[12:13], v[18:19], v[62:63]
	s_or_b64 exec, exec, s[14:15]
	s_and_saveexec_b64 s[14:15], s[2:3]
	s_cbranch_execnz .LBB0_484

.LBB0_487:
	s_or_b64 exec, exec, s[14:15]
	s_add_i32 s18, s20, s1
	s_add_i32 s14, s18, 1
	s_waitcnt vmcnt(0)
	s_add_i32 s18, s18, 2
	ds_read_b128 v[10:13], v105 offset:272
	ds_read_b128 v[18:21], v105 offset:256
	ds_read_b128 v[14:17], v105 offset:528
	s_nop 0
	ds_read_b128 v[22:25], v105 offset:512
	s_add_i32 s14, s27, 0xab
	s_lshr_b32 s14, s14, 3
	s_and_b32 s14, s14, 0x1fc0
	v_add_u32_e32 v26, s14, v77
	v_add_u32_e32 v27, s14, v81
	v_add_u32_e32 v28, s14, v80
	v_add_u32_e32 v29, s14, v79
	s_mov_b32 s14, 0x1ffffc0
	v_and_or_b32 v26, v26, s14, v82
	v_and_or_b32 v27, v27, s14, v83
	v_and_or_b32 v28, v28, s14, v82
	v_and_or_b32 v29, v29, s14, v84
	v_lshl_or_b32 v26, v26, 7, v130
	v_lshl_or_b32 v27, v27, 7, v130
	v_lshl_or_b32 v28, v28, 7, v130
	ds_read_b128 v[92:95], v26 offset:33280
	v_lshl_or_b32 v26, v29, 7, v130
	ds_read_b128 v[34:37], v27 offset:33280
	ds_read_b128 v[30:33], v28 offset:33280
	ds_read_b128 v[26:29], v26 offset:33280
	s_addk_i32 s27, 0x156
	s_lshr_b32 s15, s27, 3
	s_waitcnt lgkmcnt(3)
	v_lshlrev_b32_e32 v96, 16, v92
	v_and_b32_e32 v97, 0xffff0000, v92
	v_lshlrev_b32_e32 v92, 16, v93
	v_and_b32_e32 v93, 0xffff0000, v93
	v_lshlrev_b32_e32 v98, 16, v94
	v_and_b32_e32 v99, 0xffff0000, v94
	v_lshlrev_b32_e32 v94, 16, v95
	v_and_b32_e32 v95, 0xffff0000, v95
	s_and_b32 s27, s15, 0x1fc0
	s_waitcnt vmcnt(3)
	v_pk_fma_f32 v[66:67], v[10:11], v[98:99], v[66:67]
	s_waitcnt vmcnt(2)
	v_pk_fma_f32 v[70:71], v[18:19], v[96:97], v[70:71]
	v_pk_fma_f32 v[68:69], v[20:21], v[92:93], v[68:69]
	v_pk_fma_f32 v[62:63], v[12:13], v[94:95], v[62:63]
	s_and_saveexec_b64 s[14:15], s[6:7]
	s_cbranch_execz .LBB0_489
	v_add_u32_e32 v91, s27, v77
	s_mov_b32 s18, 0x1ffffc0
	v_and_or_b32 v91, v91, s18, v88
	v_lshl_or_b32 v91, v91, 7, v130
	ds_read_b128 v[92:95], v91 offset:33280
	s_waitcnt lgkmcnt(0)
	v_lshlrev_b32_e32 v96, 16, v92
	v_and_b32_e32 v97, 0xffff0000, v92
	v_lshlrev_b32_e32 v92, 16, v93
	v_and_b32_e32 v93, 0xffff0000, v93
	s_waitcnt vmcnt(0)
	v_pk_fma_f32 v[68:69], v[24:25], v[92:93], v[68:69]
	v_lshlrev_b32_e32 v92, 16, v94
	v_and_b32_e32 v93, 0xffff0000, v94
	v_pk_fma_f32 v[66:67], v[14:15], v[92:93], v[66:67]
	v_lshlrev_b32_e32 v92, 16, v95
	v_and_b32_e32 v93, 0xffff0000, v95
	v_pk_fma_f32 v[70:71], v[22:23], v[96:97], v[70:71]
	v_pk_fma_f32 v[62:63], v[16:17], v[92:93], v[62:63]

.LBB0_535:
	s_and_b64 vcc, exec, s[0:1]
	s_cbranch_vccz .LBB0_539
	s_add_i32 s88, s88, 0xf800
	s_sext_i32_i16 s0, s88
	s_mulk_i32 s0, 0x7879
	s_lshr_b32 s1, s0, 31
	s_ashr_i32 s0, s0, 19
	s_add_i32 s2, s0, s1
	v_mov_b32_e32 v1, v0
	s_mul_i32 s0, s2, 17
	s_sub_i32 s3, s88, s0
	s_waitcnt vmcnt(0)
	v_and_b32_e32 v2, 0xffffffcf, v1
	v_and_b32_e32 v85, 15, v1
	v_ashrrev_i32_e32 v3, 31, v2
	s_sext_i32_i16 s4, s3
	v_lshlrev_b64 v[4:5], 9, v[2:3]
	v_lshlrev_b32_e32 v3, 4, v85
	v_lshl_or_b32 v8, s4, 10, v3
	v_or_b32_e32 v10, 0x300, v8
	v_ashrrev_i32_e32 v11, 31, v10
	v_lshlrev_b64 v[10:11], 5, v[10:11]
	s_sext_i32_i16 s5, s2
	v_mov_b32_e32 v3, 0x88000
	s_bfe_i64 s[0:1], s[2:3], 0x100000
	v_mad_i64_i32 v[10:11], s[2:3], s5, v3, v[10:11]
	v_and_b32_e32 v12, 48, v1
	v_or_b32_e32 v10, v10, v12
	v_lshl_add_u64 v[66:67], s[86:87], 0, v[10:11]
	v_or_b32_e32 v10, 0x200, v8
	v_ashrrev_i32_e32 v11, 31, v10
	v_lshlrev_b64 v[10:11], 5, v[10:11]
	v_mad_i64_i32 v[10:11], s[2:3], s5, v3, v[10:11]
	s_lshl_b64 s[6:7], s[0:1], 17
	v_or_b32_e32 v10, v10, v12
	v_lshl_add_u64 v[68:69], s[86:87], 0, v[10:11]
	v_or_b32_e32 v10, 0x100, v8
	v_lshl_add_u64 v[4:5], s[6:7], 0, v[4:5]
	v_ashrrev_i32_e32 v11, 31, v10
	v_ashrrev_i32_e32 v9, 31, v8
	v_or_b32_e32 v4, v4, v12
	v_lshlrev_b64 v[10:11], 5, v[10:11]
	v_lshlrev_b64 v[8:9], 5, v[8:9]
	v_lshl_add_u64 v[74:75], s[86:87], 0, v[4:5]
	v_or_b32_e32 v4, 16, v2
	v_or_b32_e32 v2, 32, v2
	v_mad_i64_i32 v[10:11], s[2:3], s5, v3, v[10:11]
	v_mad_i64_i32 v[8:9], s[2:3], s5, v3, v[8:9]
	v_ashrrev_i32_e32 v3, 31, v2
	v_or_b32_e32 v6, 48, v1
	v_lshlrev_b64 v[2:3], 9, v[2:3]
	v_ashrrev_i32_e32 v7, 31, v6
	v_lshl_add_u64 v[2:3], s[6:7], 0, v[2:3]
	v_lshlrev_b64 v[6:7], 9, v[6:7]
	v_ashrrev_i32_e32 v5, 31, v4
	v_or_b32_e32 v2, v2, v12
	v_lshlrev_b64 v[4:5], 9, v[4:5]
	v_lshl_add_u64 v[78:79], s[86:87], 0, v[2:3]
	v_lshl_add_u64 v[2:3], s[6:7], 0, v[6:7]
	v_lshl_add_u64 v[4:5], s[6:7], 0, v[4:5]
	v_or_b32_e32 v2, v2, v12
	v_or_b32_e32 v10, v10, v12
	v_or_b32_e32 v8, v8, v12
	v_or_b32_e32 v4, v4, v12
	v_lshl_add_u64 v[80:81], s[86:87], 0, v[2:3]
	v_mov_b32_e32 v2, 0
	v_lshrrev_b32_e32 v84, 4, v1
	v_lshl_add_u64 v[70:71], s[86:87], 0, v[10:11]
	v_lshl_add_u64 v[72:73], s[86:87], 0, v[8:9]
	v_lshl_add_u64 v[76:77], s[86:87], 0, v[4:5]
	s_mul_i32 s64, s5, 0x88000
	s_lshl_b32 s65, s4, 15
	s_add_u32 s64, s64, s65
	s_add_u32 s62, s86, s64
	s_addc_u32 s63, s87, 0
	s_add_u32 s62, s62, 0x2bf1100
	s_addc_u32 s63, s63, 0
	v_lshlrev_b32_e32 v230, 4, v1
	v_lshrrev_b32_e32 v229, 5, v1
	v_mul_u32_u24_e32 v229, 0x210, v229
	v_and_b32_e32 v231, 31, v1
	v_lshl_add_u32 v229, v231, 4, v229
	v_and_b32_e32 v228, 15, v1
	v_mul_u32_u24_e32 v228, 0x210, v228
	v_bfe_u32 v231, v1, 4, 2
	v_lshl_add_u32 v228, v231, 4, v228
	global_load_dwordx4 v[14:17], v230, s[62:63]
	v_add_u32_e32 v230, 0x1000, v230
	global_load_dwordx4 v[18:21], v230, s[62:63]
	v_add_u32_e32 v230, 0x1000, v230
	global_load_dwordx4 v[22:25], v230, s[62:63]
	v_add_u32_e32 v230, 0x1000, v230
	global_load_dwordx4 v[26:29], v230, s[62:63]
	v_add_u32_e32 v230, 0x1000, v230
	global_load_dwordx4 v[30:33], v230, s[62:63]
	v_add_u32_e32 v230, 0x1000, v230
	global_load_dwordx4 v[34:37], v230, s[62:63]
	v_add_u32_e32 v230, 0x1000, v230
	global_load_dwordx4 v[38:41], v230, s[62:63]
	v_add_u32_e32 v230, 0x1000, v230
	global_load_dwordx4 v[42:45], v230, s[62:63]
	s_waitcnt vmcnt(0)
	ds_write_b128 v229, v[14:17]
	ds_write_b128 v229, v[18:21] offset:4224
	ds_write_b128 v229, v[22:25] offset:8448
	ds_write_b128 v229, v[26:29] offset:12672
	ds_write_b128 v229, v[30:33] offset:16896
	ds_write_b128 v229, v[34:37] offset:21120
	ds_write_b128 v229, v[38:41] offset:25344
	ds_write_b128 v229, v[42:45] offset:29568
	s_waitcnt lgkmcnt(0)
	s_barrier
	s_mov_b64 s[2:3], 0
	v_mov_b32_e32 v3, v2
	v_mov_b32_e32 v4, v2
	v_mov_b32_e32 v5, v2
	v_mov_b32_e32 v6, v2
	v_mov_b32_e32 v7, v2
	v_mov_b32_e32 v8, v2
	v_mov_b32_e32 v9, v2
	v_mov_b32_e32 v10, v2
	v_mov_b32_e32 v11, v2
	v_mov_b32_e32 v12, v2
	v_mov_b32_e32 v13, v2
	v_mov_b32_e32 v38, v2
	v_mov_b32_e32 v39, v2
	v_mov_b32_e32 v40, v2
	v_mov_b32_e32 v41, v2
	v_mov_b32_e32 v50, v2
	v_mov_b32_e32 v51, v2
	v_mov_b32_e32 v52, v2
	v_mov_b32_e32 v53, v2
	v_mov_b32_e32 v54, v2
	v_mov_b32_e32 v55, v2
	v_mov_b32_e32 v56, v2
	v_mov_b32_e32 v57, v2
	v_mov_b32_e32 v58, v2
	v_mov_b32_e32 v59, v2
	v_mov_b32_e32 v60, v2
	v_mov_b32_e32 v61, v2
	v_mov_b32_e32 v62, v2
	v_mov_b32_e32 v63, v2
	v_mov_b32_e32 v64, v2
	v_mov_b32_e32 v65, v2
	v_mov_b32_e32 v46, v2
	v_mov_b32_e32 v47, v2
	v_mov_b32_e32 v48, v2
	v_mov_b32_e32 v49, v2
	v_mov_b32_e32 v42, v2
	v_mov_b32_e32 v43, v2
	v_mov_b32_e32 v44, v2
	v_mov_b32_e32 v45, v2
	v_mov_b32_e32 v34, v2
	v_mov_b32_e32 v35, v2
	v_mov_b32_e32 v36, v2
	v_mov_b32_e32 v37, v2
	v_mov_b32_e32 v26, v2
	v_mov_b32_e32 v27, v2
	v_mov_b32_e32 v28, v2
	v_mov_b32_e32 v29, v2
	v_mov_b32_e32 v30, v2
	v_mov_b32_e32 v31, v2
	v_mov_b32_e32 v32, v2
	v_mov_b32_e32 v33, v2
	v_mov_b32_e32 v22, v2
	v_mov_b32_e32 v23, v2
	v_mov_b32_e32 v24, v2
	v_mov_b32_e32 v25, v2
	v_mov_b32_e32 v18, v2
	v_mov_b32_e32 v19, v2
	v_mov_b32_e32 v20, v2
	v_mov_b32_e32 v21, v2
	v_mov_b32_e32 v14, v2
	v_mov_b32_e32 v15, v2
	v_mov_b32_e32 v16, v2
	v_mov_b32_e32 v17, v2
	s_mov_b32 s5, 0x9771000
	s_mov_b32 s6, 0x2bf1000
.LBB0_537:
	v_lshl_add_u64 v[140:141], v[74:75], 0, s[2:3]
	v_add_co_u32_e32 v130, vcc, s5, v140
	v_lshl_add_u64 v[142:143], v[76:77], 0, s[2:3]
	s_nop 0
	v_addc_co_u32_e32 v134, vcc, 0, v141, vcc
	v_add_co_u32_e32 v137, vcc, s5, v142
	v_lshl_add_u64 v[140:141], v[78:79], 0, s[2:3]
	s_nop 0
	v_addc_co_u32_e32 v144, vcc, 0, v143, vcc
	v_add_co_u32_e32 v142, vcc, s5, v140
	v_lshl_add_u64 v[146:147], v[80:81], 0, s[2:3]
	s_nop 0
	v_addc_co_u32_e32 v143, vcc, 0, v141, vcc
	v_add_co_u32_e32 v140, vcc, s5, v146
	v_lshl_add_u64 v[148:149], v[72:73], 0, s[2:3]
	s_nop 0
	v_addc_co_u32_e32 v141, vcc, 0, v147, vcc
	v_add_co_u32_e32 v145, vcc, s6, v148
	v_lshl_add_u64 v[146:147], v[70:71], 0, s[2:3]
	s_nop 0
	v_addc_co_u32_e32 v150, vcc, 0, v149, vcc
	v_add_co_u32_e32 v148, vcc, s6, v146
	v_lshl_add_u64 v[152:153], v[68:69], 0, s[2:3]
	s_nop 0
	v_addc_co_u32_e32 v149, vcc, 0, v147, vcc
	v_add_co_u32_e32 v146, vcc, s6, v152
	v_lshl_add_u64 v[154:155], v[66:67], 0, s[2:3]
	s_nop 0
	v_addc_co_u32_e32 v147, vcc, 0, v153, vcc
	v_add_co_u32_e32 v151, vcc, s6, v154
	s_nop 1
	v_addc_co_u32_e32 v152, vcc, 0, v155, vcc
	v_mov_b32_e32 v154, v130
	v_mov_b32_e32 v155, v134
	global_load_dwordx4 v[156:159], v[154:155], off offset:320
	v_mov_b32_e32 v154, v137
	v_mov_b32_e32 v155, v144
	global_load_dwordx4 v[162:165], v[154:155], off offset:320
	global_load_dwordx4 v[168:171], v[142:143], off offset:320
	global_load_dwordx4 v[174:177], v[140:141], off offset:320
	v_mov_b32_e32 v140, v145
	v_mov_b32_e32 v141, v150
	ds_read_b128 v[180:183], v228 offset:64
	ds_read_b128 v[140:143], v228 offset:8512
	ds_read_b128 v[184:187], v228 offset:16960
	v_mov_b32_e32 v144, v151
	v_mov_b32_e32 v145, v152
	ds_read_b128 v[146:149], v228 offset:25408
	v_lshl_add_u64 v[82:83], v[74:75], 0, s[2:3]
	v_add_co_u32_e32 v82, vcc, s5, v82
	v_lshl_add_u64 v[90:91], v[76:77], 0, s[2:3]
	s_nop 0
	v_addc_co_u32_e32 v83, vcc, 0, v83, vcc
	v_add_co_u32_e32 v118, vcc, s5, v90
	v_lshl_add_u64 v[94:95], v[78:79], 0, s[2:3]
	s_nop 0
	v_addc_co_u32_e32 v119, vcc, 0, v91, vcc
	v_add_co_u32_e32 v120, vcc, s5, v94
	v_lshl_add_u64 v[98:99], v[80:81], 0, s[2:3]
	s_nop 0
	v_addc_co_u32_e32 v121, vcc, 0, v95, vcc
	v_add_co_u32_e32 v122, vcc, s5, v98
	v_lshl_add_u64 v[102:103], v[72:73], 0, s[2:3]
	s_nop 0
	v_addc_co_u32_e32 v123, vcc, 0, v99, vcc
	v_add_co_u32_e32 v124, vcc, s6, v102
	v_lshl_add_u64 v[106:107], v[70:71], 0, s[2:3]
	s_nop 0
	v_addc_co_u32_e32 v125, vcc, 0, v103, vcc
	v_add_co_u32_e32 v126, vcc, s6, v106
	v_lshl_add_u64 v[110:111], v[68:69], 0, s[2:3]
	s_nop 0
	v_addc_co_u32_e32 v127, vcc, 0, v107, vcc
	global_load_dwordx4 v[86:89], v[82:83], off offset:256
	global_load_dwordx4 v[90:93], v[118:119], off offset:256
	global_load_dwordx4 v[94:97], v[120:121], off offset:256
	global_load_dwordx4 v[98:101], v[122:123], off offset:256
	v_add_co_u32_e32 v128, vcc, s6, v110
	v_lshl_add_u64 v[114:115], v[66:67], 0, s[2:3]
	s_nop 0
	v_addc_co_u32_e32 v129, vcc, 0, v111, vcc
	v_add_co_u32_e32 v138, vcc, s6, v114
	ds_read_b128 v[102:105], v228
	ds_read_b128 v[106:109], v228 offset:8448
	v_addc_co_u32_e32 v139, vcc, 0, v115, vcc
	ds_read_b128 v[110:113], v228 offset:16896
	ds_read_b128 v[114:117], v228 offset:25344
	s_add_u32 s2, s2, 0x80
	s_addc_u32 s3, s3, 0
	s_cmpk_lg_i32 s2, 0x200
	s_waitcnt vmcnt(0) lgkmcnt(0)
	v_mfma_f32_16x16x32_bf16 v[62:65], v[86:89], v[102:105], v[62:65]
	s_waitcnt vmcnt(2)
	v_mfma_f32_16x16x32_bf16 v[58:61], v[86:89], v[106:109], v[58:61]
	s_waitcnt vmcnt(1)
	v_mfma_f32_16x16x32_bf16 v[54:57], v[86:89], v[110:113], v[54:57]
	s_waitcnt vmcnt(0)
	v_mfma_f32_16x16x32_bf16 v[50:53], v[86:89], v[114:117], v[50:53]
	v_mfma_f32_16x16x32_bf16 v[38:41], v[90:93], v[102:105], v[38:41]
	v_mfma_f32_16x16x32_bf16 v[10:13], v[90:93], v[106:109], v[10:13]
	v_mfma_f32_16x16x32_bf16 v[6:9], v[90:93], v[110:113], v[6:9]
	v_mfma_f32_16x16x32_bf16 v[2:5], v[90:93], v[114:117], v[2:5]
	v_mfma_f32_16x16x32_bf16 v[46:49], v[94:97], v[102:105], v[46:49]
	v_mfma_f32_16x16x32_bf16 v[42:45], v[94:97], v[106:109], v[42:45]
	v_mfma_f32_16x16x32_bf16 v[34:37], v[94:97], v[110:113], v[34:37]
	v_mfma_f32_16x16x32_bf16 v[26:29], v[94:97], v[114:117], v[26:29]
	v_mfma_f32_16x16x32_bf16 v[30:33], v[98:101], v[102:105], v[30:33]
	v_mfma_f32_16x16x32_bf16 v[22:25], v[98:101], v[106:109], v[22:25]
	v_mfma_f32_16x16x32_bf16 v[18:21], v[98:101], v[110:113], v[18:21]
	v_mfma_f32_16x16x32_bf16 v[14:17], v[98:101], v[114:117], v[14:17]
	s_waitcnt vmcnt(0)
	v_mfma_f32_16x16x32_bf16 v[62:65], v[156:159], v[180:183], v[62:65]
	v_mfma_f32_16x16x32_bf16 v[58:61], v[156:159], v[140:143], v[58:61]
	v_mfma_f32_16x16x32_bf16 v[54:57], v[156:159], v[184:187], v[54:57]
	v_mfma_f32_16x16x32_bf16 v[50:53], v[156:159], v[146:149], v[50:53]
	v_mfma_f32_16x16x32_bf16 v[38:41], v[162:165], v[180:183], v[38:41]
	v_mfma_f32_16x16x32_bf16 v[10:13], v[162:165], v[140:143], v[10:13]
	v_mfma_f32_16x16x32_bf16 v[6:9], v[162:165], v[184:187], v[6:9]
	v_mfma_f32_16x16x32_bf16 v[2:5], v[162:165], v[146:149], v[2:5]
	v_mfma_f32_16x16x32_bf16 v[46:49], v[168:171], v[180:183], v[46:49]
	v_mfma_f32_16x16x32_bf16 v[42:45], v[168:171], v[140:143], v[42:45]
	v_mfma_f32_16x16x32_bf16 v[34:37], v[168:171], v[184:187], v[34:37]
	v_mfma_f32_16x16x32_bf16 v[26:29], v[168:171], v[146:149], v[26:29]
	v_mfma_f32_16x16x32_bf16 v[30:33], v[174:177], v[180:183], v[30:33]
	v_mfma_f32_16x16x32_bf16 v[22:25], v[174:177], v[140:143], v[22:25]
	v_mfma_f32_16x16x32_bf16 v[18:21], v[174:177], v[184:187], v[18:21]
	v_mfma_f32_16x16x32_bf16 v[14:17], v[174:177], v[146:149], v[14:17]
	v_add_u32_e32 v228, 0x80, v228
	s_cbranch_scc1 .LBB0_537
	v_and_b32_e32 v66, 3, v84
	v_and_b32_e32 v1, 0xffffffc0, v1
	s_lshl_b64 s[0:1], s[0:1], 9
	v_readlane_b32 s2, v254, 9
	v_lshl_or_b32 v66, v66, 2, v1
	v_lshl_or_b32 v68, s4, 6, v85
	v_readlane_b32 s3, v254, 10
	s_add_u32 s0, s2, s0
	s_addc_u32 s1, s3, s1
	v_ashrrev_i32_e32 v67, 31, v66
	v_ashrrev_i32_e32 v69, 31, v68
	v_lshl_add_u64 v[66:67], v[66:67], 1, s[0:1]
	v_cvt_pk_bf16_f32 v62, v62, v63
	v_cvt_pk_bf16_f32 v63, v64, v65
	v_lshlrev_b64 v[64:65], 14, v[68:69]
	v_lshl_add_u64 v[64:65], v[66:67], 0, v[64:65]
	global_store_dwordx2 v[64:65], v[62:63], off
	v_or_b32_e32 v62, 16, v68
	v_ashrrev_i32_e32 v63, 31, v62
	v_cvt_pk_bf16_f32 v58, v58, v59
	v_cvt_pk_bf16_f32 v59, v60, v61
	v_lshlrev_b64 v[60:61], 14, v[62:63]
	v_lshl_add_u64 v[60:61], v[66:67], 0, v[60:61]
	global_store_dwordx2 v[60:61], v[58:59], off
	v_or_b32_e32 v58, 32, v68
	v_ashrrev_i32_e32 v59, 31, v58
	v_cvt_pk_bf16_f32 v54, v54, v55
	v_cvt_pk_bf16_f32 v55, v56, v57
	v_lshlrev_b64 v[56:57], 14, v[58:59]
	v_lshl_add_u64 v[56:57], v[66:67], 0, v[56:57]
	global_store_dwordx2 v[56:57], v[54:55], off
	v_or_b32_e32 v54, 48, v68
	v_ashrrev_i32_e32 v55, 31, v54
	v_cvt_pk_bf16_f32 v50, v50, v51
	v_cvt_pk_bf16_f32 v51, v52, v53
	v_lshlrev_b64 v[52:53], 14, v[54:55]
	v_lshl_add_u64 v[52:53], v[66:67], 0, v[52:53]
	v_cvt_pk_bf16_f32 v2, v2, v3
	v_cvt_pk_bf16_f32 v3, v4, v5
	global_store_dwordx2 v[52:53], v[2:3], off offset:32
	v_cvt_pk_bf16_f32 v2, v46, v47
	v_cvt_pk_bf16_f32 v3, v48, v49
	global_store_dwordx2 v[64:65], v[2:3], off offset:64
	v_cvt_pk_bf16_f32 v2, v42, v43
	v_cvt_pk_bf16_f32 v3, v44, v45
	global_store_dwordx2 v[60:61], v[2:3], off offset:64
	v_cvt_pk_bf16_f32 v2, v34, v35
	v_cvt_pk_bf16_f32 v3, v36, v37
	global_store_dwordx2 v[56:57], v[2:3], off offset:64
	v_cvt_pk_bf16_f32 v2, v26, v27
	v_cvt_pk_bf16_f32 v3, v28, v29
	global_store_dwordx2 v[52:53], v[2:3], off offset:64
	v_cvt_pk_bf16_f32 v2, v30, v31
	v_cvt_pk_bf16_f32 v3, v32, v33
	global_store_dwordx2 v[64:65], v[2:3], off offset:96
	v_cvt_pk_bf16_f32 v2, v22, v23
	v_cvt_pk_bf16_f32 v3, v24, v25
	global_store_dwordx2 v[60:61], v[2:3], off offset:96
	v_cvt_pk_bf16_f32 v2, v18, v19
	v_cvt_pk_bf16_f32 v3, v20, v21
	v_cvt_pk_bf16_f32 v38, v38, v39
	v_cvt_pk_bf16_f32 v39, v40, v41
	v_cvt_pk_bf16_f32 v10, v10, v11
	v_cvt_pk_bf16_f32 v11, v12, v13
	v_cvt_pk_bf16_f32 v6, v6, v7
	v_cvt_pk_bf16_f32 v7, v8, v9
	global_store_dwordx2 v[56:57], v[2:3], off offset:96
	v_cvt_pk_bf16_f32 v2, v14, v15
	v_cvt_pk_bf16_f32 v3, v16, v17
	global_store_dwordx2 v[52:53], v[50:51], off
	global_store_dwordx2 v[64:65], v[38:39], off offset:32
	global_store_dwordx2 v[60:61], v[10:11], off offset:32
	global_store_dwordx2 v[56:57], v[6:7], off offset:32
	global_store_dwordx2 v[52:53], v[2:3], off offset:96
